# GEMM K-loop: B-fragment LDS reads of phases 1/5 interleaved into the MFMA cluster of phases 8/4
# speedup vs baseline: 1.0188x; 1.0188x over previous
; #define PG8_STAGE(bufoff, gbase, voff) do { _Pragma("unroll") for (int _i = 0; _i < 2; ++_i) \
;         __builtin_amdgcn_global_load_lds((const unsigned*)((const char*)(gbase) + (voff)[_i]), (LAS unsigned*)(lds + (bufoff) + ldsw + _i * 8192), 16, 0, 0); } while (0)
; #define PG8_LDA(dst, b, h) do { _Pragma("unroll") for (int m = 0; m < 4; ++m) _Pragma("unroll") for (int k = 0; k < 2; ++k) dst[m][k] = *(const LAS bf16x8*)(lds + PG8_SA(b, h) + aoff + m * 2048 + k * 1024); } while (0)
; #define PG8_LDB(dst, b, h) do { _Pragma("unroll") for (int n = 0; n < 2; ++n) _Pragma("unroll") for (int k = 0; k < 2; ++k) dst[n][k] = *(const LAS bf16x8*)(lds + PG8_SB(b, h) + boff + n * 2048 + k * 1024); } while (0)
; #define PG8_MMA(ai, bj, At, Bt) do { __builtin_amdgcn_s_setprio(1); _Pragma("unroll") for (int m = 0; m < 4; ++m) _Pragma("unroll") for (int n = 0; n < 2; ++n) _Pragma("unroll") for (int k = 0; k < 2; ++k) \
;         acc[ai][bj][m][n] = __builtin_amdgcn_mfma_f32_16x16x32_bf16(Bt[n][k], At[m][k], acc[ai][bj][m][n], 0, 0, 0); __builtin_amdgcn_s_setprio(0); } while (0)
; #define PG8_WAIT_V(n) asm volatile("s_waitcnt vmcnt(" #n ")" ::: "memory")
; #define PG8_WAIT_L(n) asm volatile("s_waitcnt lgkmcnt(" #n ")" ::: "memory")
; #define PG8_BAR __builtin_amdgcn_s_barrier()
; #define PG8_SCHED __builtin_amdgcn_sched_barrier(0)
; template <class Epi, class Sched>
; __device__ __forceinline__ void gemm_phase(LAS unsigned char* lds, const Gemm g, const Sched& S, const Epi& E) {
;     ...
;             PG8_LDB(B0, 0, 0); PG8_SCHED; PG8_LDA(At, 0, 0); PG8_STAGE(PG8_SA(1, 1), a1 + hstep, voffA);
;             PG8_WAIT_L(8); PG8_BAR; PG8_WAIT_L(0); PG8_MMA(0, 0, At, B0); PG8_BAR; PG8_SCHED;
;             PG8_LDB(B1, 0, 1); PG8_STAGE(PG8_SB(0, 0), b2, voffB);
;             PG8_BAR; PG8_WAIT_L(0); PG8_MMA(0, 1, At, B1); PG8_BAR;
;             PG8_LDA(At, 0, 1); PG8_STAGE(PG8_SA(0, 0), a2, voffA);
;             PG8_BAR; PG8_WAIT_L(0); PG8_MMA(1, 0, At, B0); PG8_BAR; PG8_SCHED;
;             PG8_STAGE(PG8_SB(0, 1), b2 + hstep, voffB);
;             PG8_WAIT_V(6); PG8_BAR; PG8_MMA(1, 1, At, B1); PG8_BAR;
.LBB0_187:
	s_add_u32 s20, s72, 0xfffc0080
	s_addc_u32 s21, s73, -1
	s_add_i32 s22, 16, 0x10000
	v_add_u32_e32 v153, s22, v154
	s_cmp_eq_u32 s19, 12
	s_cselect_b32 s71, s41, s21
	s_cselect_b32 s70, s78, s20
	s_cselect_b32 s67, s1, s18
	s_cselect_b32 s66, s16, s17
	v_lshl_add_u64 v[216:217], s[72:73], 0, v[148:149]
	s_add_i32 m0, s9, 0xc000
	ds_read_b128 v[172:175], v155
	ds_read_b128 v[188:191], v155 offset:1024
	ds_read_b128 v[192:195], v155 offset:2048
	ds_read_b128 v[196:199], v155 offset:3072
	ds_read_b128 v[200:203], v155 offset:4096
	ds_read_b128 v[204:207], v155 offset:5120
	ds_read_b128 v[208:211], v155 offset:6144
	ds_read_b128 v[212:215], v155 offset:7168
	global_load_lds_dwordx4 v[216:217], off
	v_lshl_add_u64 v[216:217], s[72:73], 0, v[150:151]
	s_add_i32 m0, s9, 0xe000
	s_nop 0
	global_load_lds_dwordx4 v[216:217], off
	s_waitcnt lgkmcnt(8)
	s_barrier
	s_waitcnt lgkmcnt(0)
	s_setprio 1
	s_waitcnt lgkmcnt(0)
	v_mfma_f32_16x16x32_bf16 v[126:129], v[156:159], v[172:175], v[126:129]
	v_mfma_f32_16x16x32_bf16 v[122:125], v[164:167], v[172:175], v[122:125]
	v_mfma_f32_16x16x32_bf16 v[118:121], v[156:159], v[192:195], v[118:121]
	v_mfma_f32_16x16x32_bf16 v[110:113], v[164:167], v[192:195], v[110:113]
	v_mfma_f32_16x16x32_bf16 v[102:105], v[156:159], v[200:203], v[102:105]
	v_mfma_f32_16x16x32_bf16 v[94:97], v[164:167], v[200:203], v[94:97]
	v_mfma_f32_16x16x32_bf16 v[86:89], v[156:159], v[208:211], v[86:89]
	v_mfma_f32_16x16x32_bf16 v[78:81], v[164:167], v[208:211], v[78:81]
	v_mfma_f32_16x16x32_bf16 v[126:129], v[160:163], v[188:191], v[126:129]
	v_mfma_f32_16x16x32_bf16 v[122:125], v[168:171], v[188:191], v[122:125]
	v_mfma_f32_16x16x32_bf16 v[118:121], v[160:163], v[196:199], v[118:121]
	v_mfma_f32_16x16x32_bf16 v[110:113], v[168:171], v[196:199], v[110:113]
	v_mfma_f32_16x16x32_bf16 v[102:105], v[160:163], v[204:207], v[102:105]
	v_mfma_f32_16x16x32_bf16 v[94:97], v[168:171], v[204:207], v[94:97]
	v_mfma_f32_16x16x32_bf16 v[86:89], v[160:163], v[212:215], v[86:89]
	v_mfma_f32_16x16x32_bf16 v[78:81], v[168:171], v[212:215], v[78:81]
	s_setprio 0
	s_barrier
	s_add_i32 s23, 16, 0x14000
	s_add_i32 s20, s22, s8
	v_add_u32_e32 v153, s23, v154
	v_lshl_add_u64 v[232:233], s[66:67], 0, v[144:145]
	s_mov_b32 m0, s20
	ds_read_b128 v[216:219], v153
	ds_read_b128 v[220:223], v153 offset:1024
	ds_read_b128 v[224:227], v153 offset:2048
	ds_read_b128 v[228:231], v153 offset:3072
	global_load_lds_dwordx4 v[232:233], off
	v_lshl_add_u64 v[234:235], s[66:67], 0, v[140:141]
	s_add_i32 m0, s20, 0x2000
	s_nop 0
	global_load_lds_dwordx4 v[234:235], off
	s_barrier
	s_waitcnt lgkmcnt(0)
	s_setprio 1
	s_waitcnt lgkmcnt(0)
	v_mfma_f32_16x16x32_bf16 v[114:117], v[216:219], v[172:175], v[114:117]
	v_mfma_f32_16x16x32_bf16 v[106:109], v[224:227], v[172:175], v[106:109]
	v_mfma_f32_16x16x32_bf16 v[98:101], v[216:219], v[192:195], v[98:101]
	v_mfma_f32_16x16x32_bf16 v[90:93], v[224:227], v[192:195], v[90:93]
	v_mfma_f32_16x16x32_bf16 v[82:85], v[216:219], v[200:203], v[82:85]
	v_mfma_f32_16x16x32_bf16 v[74:77], v[224:227], v[200:203], v[74:77]
	v_mfma_f32_16x16x32_bf16 v[70:73], v[216:219], v[208:211], v[70:73]
	v_mfma_f32_16x16x32_bf16 v[66:69], v[224:227], v[208:211], v[66:69]
	v_mfma_f32_16x16x32_bf16 v[114:117], v[220:223], v[188:191], v[114:117]
	v_mfma_f32_16x16x32_bf16 v[106:109], v[228:231], v[188:191], v[106:109]
	v_mfma_f32_16x16x32_bf16 v[98:101], v[220:223], v[196:199], v[98:101]
	v_mfma_f32_16x16x32_bf16 v[90:93], v[228:231], v[196:199], v[90:93]
	v_mfma_f32_16x16x32_bf16 v[82:85], v[220:223], v[204:207], v[82:85]
	v_mfma_f32_16x16x32_bf16 v[74:77], v[228:231], v[204:207], v[74:77]
	v_mfma_f32_16x16x32_bf16 v[70:73], v[220:223], v[212:215], v[70:73]
	v_mfma_f32_16x16x32_bf16 v[66:69], v[228:231], v[212:215], v[66:69]
	s_setprio 0
	s_mov_b32 m0, s9
	v_lshl_add_u64 v[236:237], s[70:71], 0, v[146:147]
	s_barrier
	ds_read_b128 v[172:175], v155 offset:16384
	ds_read_b128 v[188:191], v155 offset:17408
	ds_read_b128 v[192:195], v155 offset:18432
	ds_read_b128 v[196:199], v155 offset:19456
	ds_read_b128 v[200:203], v155 offset:20480
	ds_read_b128 v[204:207], v155 offset:21504
	ds_read_b128 v[208:211], v155 offset:22528
	ds_read_b128 v[212:215], v155 offset:23552
	global_load_lds_dwordx4 v[236:237], off
	v_lshl_add_u64 v[238:239], s[70:71], 0, v[142:143]
	s_mov_b32 m0, s10
	s_nop 0
	global_load_lds_dwordx4 v[238:239], off
	s_barrier
	s_waitcnt lgkmcnt(0)
	s_setprio 1
	s_waitcnt lgkmcnt(0)
	v_mfma_f32_16x16x32_bf16 v[62:65], v[156:159], v[172:175], v[62:65]
	v_mfma_f32_16x16x32_bf16 v[58:61], v[164:167], v[172:175], v[58:61]
	v_mfma_f32_16x16x32_bf16 v[54:57], v[156:159], v[192:195], v[54:57]
	v_mfma_f32_16x16x32_bf16 v[50:53], v[164:167], v[192:195], v[50:53]
	v_mfma_f32_16x16x32_bf16 v[38:41], v[156:159], v[200:203], v[38:41]
	v_mfma_f32_16x16x32_bf16 v[34:37], v[164:167], v[200:203], v[34:37]
	v_mfma_f32_16x16x32_bf16 v[22:25], v[156:159], v[208:211], v[22:25]
	v_mfma_f32_16x16x32_bf16 v[18:21], v[164:167], v[208:211], v[18:21]
	v_mfma_f32_16x16x32_bf16 v[62:65], v[160:163], v[188:191], v[62:65]
	v_mfma_f32_16x16x32_bf16 v[58:61], v[168:171], v[188:191], v[58:61]
	v_mfma_f32_16x16x32_bf16 v[54:57], v[160:163], v[196:199], v[54:57]
	v_mfma_f32_16x16x32_bf16 v[50:53], v[168:171], v[196:199], v[50:53]
	v_mfma_f32_16x16x32_bf16 v[38:41], v[160:163], v[204:207], v[38:41]
	v_mfma_f32_16x16x32_bf16 v[34:37], v[168:171], v[204:207], v[34:37]
	v_mfma_f32_16x16x32_bf16 v[22:25], v[160:163], v[212:215], v[22:25]
	v_mfma_f32_16x16x32_bf16 v[18:21], v[168:171], v[212:215], v[18:21]
	s_setprio 0
	s_barrier
; #define PG8_STAGE(bufoff, gbase, voff) do { _Pragma("unroll") for (int _i = 0; _i < 2; ++_i) \
;         __builtin_amdgcn_global_load_lds((const unsigned*)((const char*)(gbase) + (voff)[_i]), (LAS unsigned*)(lds + (bufoff) + ldsw + _i * 8192), 16, 0, 0); } while (0)
; #define PG8_LDA(dst, b, h) do { _Pragma("unroll") for (int m = 0; m < 4; ++m) _Pragma("unroll") for (int k = 0; k < 2; ++k) dst[m][k] = *(const LAS bf16x8*)(lds + PG8_SA(b, h) + aoff + m * 2048 + k * 1024); } while (0)
; #define PG8_LDB(dst, b, h) do { _Pragma("unroll") for (int n = 0; n < 2; ++n) _Pragma("unroll") for (int k = 0; k < 2; ++k) dst[n][k] = *(const LAS bf16x8*)(lds + PG8_SB(b, h) + boff + n * 2048 + k * 1024); } while (0)
; #define PG8_MMA(ai, bj, At, Bt) do { __builtin_amdgcn_s_setprio(1); _Pragma("unroll") for (int m = 0; m < 4; ++m) _Pragma("unroll") for (int n = 0; n < 2; ++n) _Pragma("unroll") for (int k = 0; k < 2; ++k) \
;         acc[ai][bj][m][n] = __builtin_amdgcn_mfma_f32_16x16x32_bf16(Bt[n][k], At[m][k], acc[ai][bj][m][n], 0, 0, 0); __builtin_amdgcn_s_setprio(0); } while (0)
; #define PG8_WAIT_V(n) asm volatile("s_waitcnt vmcnt(" #n ")" ::: "memory")
; #define PG8_WAIT_L(n) asm volatile("s_waitcnt lgkmcnt(" #n ")" ::: "memory")
; #define PG8_BAR __builtin_amdgcn_s_barrier()
; #define PG8_SCHED __builtin_amdgcn_sched_barrier(0)
; template <class Epi, class Sched>
; __device__ __forceinline__ void gemm_phase(LAS unsigned char* lds, const Gemm g, const Sched& S, const Epi& E) {
;     ...
;             PG8_WAIT_V(6); PG8_BAR; PG8_MMA(1, 1, At, B1); PG8_BAR;
;             PG8_LDB(B0, 1, 0); PG8_SCHED; PG8_LDA(At, 1, 0); PG8_STAGE(PG8_SA(0, 1), a2 + hstep, voffA);
;             PG8_WAIT_L(8); PG8_BAR; PG8_WAIT_L(0); PG8_MMA(0, 0, At, B0); PG8_BAR; PG8_SCHED;
;             PG8_LDB(B1, 1, 1); PG8_STAGE(PG8_SB(1, 0), b3, voffB);
;             PG8_BAR; PG8_WAIT_L(0); PG8_MMA(0, 1, At, B1); PG8_BAR;
;             PG8_LDA(At, 1, 1); PG8_STAGE(PG8_SA(1, 0), a3, voffA);
;             PG8_BAR; PG8_WAIT_L(0); PG8_MMA(1, 0, At, B0); PG8_BAR; PG8_SCHED;
	s_add_u32 s20, s66, 0x40000
	s_addc_u32 s21, s67, 0
	s_add_i32 s22, s23, s8
	v_lshl_add_u64 v[156:157], s[20:21], 0, v[144:145]
	s_mov_b32 m0, s22
	s_nop 0
	global_load_lds_dwordx4 v[156:157], off
	v_lshl_add_u64 v[156:157], s[20:21], 0, v[140:141]
	s_add_i32 m0, s22, 0x2000
	s_nop 0
	global_load_lds_dwordx4 v[156:157], off
	s_waitcnt vmcnt(6)
	s_barrier
	s_setprio 1
	v_mfma_f32_16x16x32_bf16 v[46:49], v[216:219], v[172:175], v[46:49]
	v_add_u32_e32 v153, 0x18010, v154
	v_mfma_f32_16x16x32_bf16 v[42:45], v[224:227], v[172:175], v[42:45]
	ds_read_b128 v[156:159], v153
	v_mfma_f32_16x16x32_bf16 v[30:33], v[216:219], v[192:195], v[30:33]
	ds_read_b128 v[160:163], v153 offset:1024
	v_mfma_f32_16x16x32_bf16 v[26:29], v[224:227], v[192:195], v[26:29]
	ds_read_b128 v[164:167], v153 offset:2048
	v_mfma_f32_16x16x32_bf16 v[14:17], v[216:219], v[200:203], v[14:17]
	ds_read_b128 v[168:171], v153 offset:3072
	v_mfma_f32_16x16x32_bf16 v[10:13], v[224:227], v[200:203], v[10:13]
	v_mfma_f32_16x16x32_bf16 v[4:7], v[216:219], v[208:211], v[4:7]
	v_mfma_f32_16x16x32_bf16 v[0:3], v[224:227], v[208:211], v[0:3]
	v_mfma_f32_16x16x32_bf16 v[46:49], v[220:223], v[188:191], v[46:49]
	v_mfma_f32_16x16x32_bf16 v[42:45], v[228:231], v[188:191], v[42:45]
	v_mfma_f32_16x16x32_bf16 v[30:33], v[220:223], v[196:199], v[30:33]
	v_mfma_f32_16x16x32_bf16 v[26:29], v[228:231], v[196:199], v[26:29]
	v_mfma_f32_16x16x32_bf16 v[14:17], v[220:223], v[204:207], v[14:17]
	v_mfma_f32_16x16x32_bf16 v[10:13], v[228:231], v[204:207], v[10:13]
	v_mfma_f32_16x16x32_bf16 v[4:7], v[220:223], v[212:215], v[4:7]
	v_mfma_f32_16x16x32_bf16 v[0:3], v[228:231], v[212:215], v[0:3]
	s_setprio 0
	s_add_i32 s22, 16, 0x18000
	v_add_u32_e32 v153, s22, v154
	s_barrier
	s_add_u32 s20, s70, 0x40000
	s_addc_u32 s21, s71, 0
	s_mov_b32 m0, s11
	v_lshl_add_u64 v[216:217], s[20:21], 0, v[146:147]
	ds_read_b128 v[172:175], v155 offset:32768
	ds_read_b128 v[188:191], v155 offset:33792
	ds_read_b128 v[192:195], v155 offset:34816
	ds_read_b128 v[196:199], v155 offset:35840
	ds_read_b128 v[200:203], v155 offset:36864
	ds_read_b128 v[204:207], v155 offset:37888
	ds_read_b128 v[208:211], v155 offset:38912
	ds_read_b128 v[212:215], v155 offset:39936
	global_load_lds_dwordx4 v[216:217], off
	v_lshl_add_u64 v[216:217], s[20:21], 0, v[142:143]
	s_mov_b32 m0, s12
	s_nop 0
	global_load_lds_dwordx4 v[216:217], off
	s_waitcnt lgkmcnt(8)
	s_barrier
	s_waitcnt lgkmcnt(0)
	s_setprio 1
	s_waitcnt lgkmcnt(0)
	v_mfma_f32_16x16x32_bf16 v[126:129], v[156:159], v[172:175], v[126:129]
	v_mfma_f32_16x16x32_bf16 v[122:125], v[164:167], v[172:175], v[122:125]
	v_mfma_f32_16x16x32_bf16 v[118:121], v[156:159], v[192:195], v[118:121]
	v_mfma_f32_16x16x32_bf16 v[110:113], v[164:167], v[192:195], v[110:113]
	v_mfma_f32_16x16x32_bf16 v[102:105], v[156:159], v[200:203], v[102:105]
	v_mfma_f32_16x16x32_bf16 v[94:97], v[164:167], v[200:203], v[94:97]
	v_mfma_f32_16x16x32_bf16 v[86:89], v[156:159], v[208:211], v[86:89]
	v_mfma_f32_16x16x32_bf16 v[78:81], v[164:167], v[208:211], v[78:81]
	v_mfma_f32_16x16x32_bf16 v[126:129], v[160:163], v[188:191], v[126:129]
	v_mfma_f32_16x16x32_bf16 v[122:125], v[168:171], v[188:191], v[122:125]
	v_mfma_f32_16x16x32_bf16 v[118:121], v[160:163], v[196:199], v[118:121]
	v_mfma_f32_16x16x32_bf16 v[110:113], v[168:171], v[196:199], v[110:113]
	v_mfma_f32_16x16x32_bf16 v[102:105], v[160:163], v[204:207], v[102:105]
	v_mfma_f32_16x16x32_bf16 v[94:97], v[168:171], v[204:207], v[94:97]
	v_mfma_f32_16x16x32_bf16 v[86:89], v[160:163], v[212:215], v[86:89]
	v_mfma_f32_16x16x32_bf16 v[78:81], v[168:171], v[212:215], v[78:81]
	s_setprio 0
	s_barrier
	s_add_i32 s23, 16, 0x1c000
	s_add_i32 s20, s22, s8
	v_add_u32_e32 v153, s23, v154
	v_lshl_add_u64 v[232:233], v[232:233], 0, s[94:95]
	s_mov_b32 m0, s20
	ds_read_b128 v[216:219], v153
	ds_read_b128 v[220:223], v153 offset:1024
	ds_read_b128 v[224:227], v153 offset:2048
	ds_read_b128 v[228:231], v153 offset:3072
	global_load_lds_dwordx4 v[232:233], off
	v_lshl_add_u64 v[232:233], v[234:235], 0, s[94:95]
	s_add_i32 m0, s20, 0x2000
	s_nop 0
	global_load_lds_dwordx4 v[232:233], off
	s_barrier
	s_waitcnt lgkmcnt(0)
	s_setprio 1
	s_waitcnt lgkmcnt(0)
	v_mfma_f32_16x16x32_bf16 v[114:117], v[216:219], v[172:175], v[114:117]
	v_mfma_f32_16x16x32_bf16 v[106:109], v[224:227], v[172:175], v[106:109]
	v_mfma_f32_16x16x32_bf16 v[98:101], v[216:219], v[192:195], v[98:101]
	v_mfma_f32_16x16x32_bf16 v[90:93], v[224:227], v[192:195], v[90:93]
	v_mfma_f32_16x16x32_bf16 v[82:85], v[216:219], v[200:203], v[82:85]
	v_mfma_f32_16x16x32_bf16 v[74:77], v[224:227], v[200:203], v[74:77]
	v_mfma_f32_16x16x32_bf16 v[70:73], v[216:219], v[208:211], v[70:73]
	v_mfma_f32_16x16x32_bf16 v[66:69], v[224:227], v[208:211], v[66:69]
	v_mfma_f32_16x16x32_bf16 v[114:117], v[220:223], v[188:191], v[114:117]
	v_mfma_f32_16x16x32_bf16 v[106:109], v[228:231], v[188:191], v[106:109]
	v_mfma_f32_16x16x32_bf16 v[98:101], v[220:223], v[196:199], v[98:101]
	v_mfma_f32_16x16x32_bf16 v[90:93], v[228:231], v[196:199], v[90:93]
	v_mfma_f32_16x16x32_bf16 v[82:85], v[220:223], v[204:207], v[82:85]
	v_mfma_f32_16x16x32_bf16 v[74:77], v[228:231], v[204:207], v[74:77]
	v_mfma_f32_16x16x32_bf16 v[70:73], v[220:223], v[212:215], v[70:73]
	v_mfma_f32_16x16x32_bf16 v[66:69], v[228:231], v[212:215], v[66:69]
	s_setprio 0
	s_mov_b32 m0, s13
	v_lshl_add_u64 v[232:233], v[236:237], 0, s[94:95]
	s_barrier
; #define PG8_STAGE(bufoff, gbase, voff) do { _Pragma("unroll") for (int _i = 0; _i < 2; ++_i) \
;         __builtin_amdgcn_global_load_lds((const unsigned*)((const char*)(gbase) + (voff)[_i]), (LAS unsigned*)(lds + (bufoff) + ldsw + _i * 8192), 16, 0, 0); } while (0)
; #define PG8_LDA(dst, b, h) do { _Pragma("unroll") for (int m = 0; m < 4; ++m) _Pragma("unroll") for (int k = 0; k < 2; ++k) dst[m][k] = *(const LAS bf16x8*)(lds + PG8_SA(b, h) + aoff + m * 2048 + k * 1024); } while (0)
; #define PG8_MMA(ai, bj, At, Bt) do { __builtin_amdgcn_s_setprio(1); _Pragma("unroll") for (int m = 0; m < 4; ++m) _Pragma("unroll") for (int n = 0; n < 2; ++n) _Pragma("unroll") for (int k = 0; k < 2; ++k) \
;         acc[ai][bj][m][n] = __builtin_amdgcn_mfma_f32_16x16x32_bf16(Bt[n][k], At[m][k], acc[ai][bj][m][n], 0, 0, 0); __builtin_amdgcn_s_setprio(0); } while (0)
; #define PG8_WAIT_V(n) asm volatile("s_waitcnt vmcnt(" #n ")" ::: "memory")
; #define PG8_WAIT_L(n) asm volatile("s_waitcnt lgkmcnt(" #n ")" ::: "memory")
; #define PG8_BAR __builtin_amdgcn_s_barrier()
; #define PG8_SCHED __builtin_amdgcn_sched_barrier(0)
; template <class Epi, class Sched>
; __device__ __forceinline__ void gemm_phase(LAS unsigned char* lds, const Gemm g, const Sched& S, const Epi& E) {
;     ...
;             PG8_LDA(At, 1, 1); PG8_STAGE(PG8_SA(1, 0), a3, voffA);
;             PG8_BAR; PG8_WAIT_L(0); PG8_MMA(1, 0, At, B0); PG8_BAR; PG8_SCHED;
;             PG8_STAGE(PG8_SB(1, 1), b3 + hstep, voffB);
;             PG8_WAIT_V(6); PG8_BAR; PG8_MMA(1, 1, At, B1); PG8_BAR;
	ds_read_b128 v[172:175], v155 offset:49152
	ds_read_b128 v[188:191], v155 offset:50176
	ds_read_b128 v[192:195], v155 offset:51200
	ds_read_b128 v[196:199], v155 offset:52224
	ds_read_b128 v[200:203], v155 offset:53248
	ds_read_b128 v[204:207], v155 offset:54272
	ds_read_b128 v[208:211], v155 offset:55296
	ds_read_b128 v[212:215], v155 offset:56320
	global_load_lds_dwordx4 v[232:233], off
	v_lshl_add_u64 v[232:233], v[238:239], 0, s[94:95]
	s_mov_b32 m0, s74
	s_nop 0
	global_load_lds_dwordx4 v[232:233], off
	s_barrier
	s_waitcnt lgkmcnt(0)
	s_setprio 1
	s_waitcnt lgkmcnt(0)
	v_mfma_f32_16x16x32_bf16 v[62:65], v[156:159], v[172:175], v[62:65]
	v_mfma_f32_16x16x32_bf16 v[58:61], v[164:167], v[172:175], v[58:61]
	v_mfma_f32_16x16x32_bf16 v[54:57], v[156:159], v[192:195], v[54:57]
	v_mfma_f32_16x16x32_bf16 v[50:53], v[164:167], v[192:195], v[50:53]
	v_mfma_f32_16x16x32_bf16 v[38:41], v[156:159], v[200:203], v[38:41]
	v_mfma_f32_16x16x32_bf16 v[34:37], v[164:167], v[200:203], v[34:37]
	v_mfma_f32_16x16x32_bf16 v[22:25], v[156:159], v[208:211], v[22:25]
	v_mfma_f32_16x16x32_bf16 v[18:21], v[164:167], v[208:211], v[18:21]
	v_mfma_f32_16x16x32_bf16 v[62:65], v[160:163], v[188:191], v[62:65]
	v_mfma_f32_16x16x32_bf16 v[58:61], v[168:171], v[188:191], v[58:61]
	v_mfma_f32_16x16x32_bf16 v[54:57], v[160:163], v[196:199], v[54:57]
	v_mfma_f32_16x16x32_bf16 v[50:53], v[168:171], v[196:199], v[50:53]
	v_mfma_f32_16x16x32_bf16 v[38:41], v[160:163], v[204:207], v[38:41]
	v_mfma_f32_16x16x32_bf16 v[34:37], v[168:171], v[204:207], v[34:37]
	v_mfma_f32_16x16x32_bf16 v[22:25], v[160:163], v[212:215], v[22:25]
	v_mfma_f32_16x16x32_bf16 v[18:21], v[168:171], v[212:215], v[18:21]
	s_setprio 0
	s_barrier
	s_add_u32 s20, s66, 0x40080
	s_addc_u32 s21, s67, 0
	s_add_i32 s22, s23, s8
	v_lshl_add_u64 v[156:157], s[20:21], 0, v[144:145]
	s_mov_b32 m0, s22
	s_nop 0
	global_load_lds_dwordx4 v[156:157], off
	v_lshl_add_u64 v[156:157], s[20:21], 0, v[140:141]
	s_add_i32 m0, s22, 0x2000
	s_nop 0
	global_load_lds_dwordx4 v[156:157], off
	s_waitcnt vmcnt(6)
	s_barrier
	s_setprio 1
	v_mfma_f32_16x16x32_bf16 v[46:49], v[216:219], v[172:175], v[46:49]
	v_add_u32_e32 v153, 0x10010, v154
	v_mfma_f32_16x16x32_bf16 v[42:45], v[224:227], v[172:175], v[42:45]
	ds_read_b128 v[156:159], v153
	v_mfma_f32_16x16x32_bf16 v[30:33], v[216:219], v[192:195], v[30:33]
	ds_read_b128 v[160:163], v153 offset:1024
	v_mfma_f32_16x16x32_bf16 v[26:29], v[224:227], v[192:195], v[26:29]
	ds_read_b128 v[164:167], v153 offset:2048
	v_mfma_f32_16x16x32_bf16 v[14:17], v[216:219], v[200:203], v[14:17]
	ds_read_b128 v[168:171], v153 offset:3072
	v_mfma_f32_16x16x32_bf16 v[10:13], v[224:227], v[200:203], v[10:13]
	v_mfma_f32_16x16x32_bf16 v[4:7], v[216:219], v[208:211], v[4:7]
	v_mfma_f32_16x16x32_bf16 v[0:3], v[224:227], v[208:211], v[0:3]
	v_mfma_f32_16x16x32_bf16 v[46:49], v[220:223], v[188:191], v[46:49]
	v_mfma_f32_16x16x32_bf16 v[42:45], v[228:231], v[188:191], v[42:45]
	v_mfma_f32_16x16x32_bf16 v[30:33], v[220:223], v[196:199], v[30:33]
	v_mfma_f32_16x16x32_bf16 v[26:29], v[228:231], v[196:199], v[26:29]
	v_mfma_f32_16x16x32_bf16 v[14:17], v[220:223], v[204:207], v[14:17]
	v_mfma_f32_16x16x32_bf16 v[10:13], v[228:231], v[204:207], v[10:13]
	v_mfma_f32_16x16x32_bf16 v[4:7], v[220:223], v[212:215], v[4:7]
	v_mfma_f32_16x16x32_bf16 v[0:3], v[228:231], v[212:215], v[0:3]
	s_setprio 0
	s_add_i32 s19, s19, 2
	s_add_u32 s72, s72, 0x100
	s_addc_u32 s73, s73, 0
	s_add_u32 s17, s17, 0x100
	s_addc_u32 s18, s18, 0
	s_cmp_gt_u32 s19, 13
	s_barrier
	s_cbranch_scc0 .LBB0_187
; __device__ __forceinline__ unsigned pk_bf16(float a, float b) { f32x2 v = {a, b}; bf2_t r = __builtin_convertvector(v, bf2_t); return __builtin_bit_cast(unsigned, r); }
; #define PG8_WAIT_V(n) asm volatile("s_waitcnt vmcnt(" #n ")" ::: "memory")
; #define PG8_BAR __builtin_amdgcn_s_barrier()
;     __device__ __forceinline__ void operator()(const f32x4 (&acc)[2][2][4][2], const Unit& u, int wr, int wc, int fr, int fq) const {
;         const int row0 = u.pm * BM + wr * 64 + fr; int colt = u.pn * BM; bf16_t* base = O;
;         if (split_cols) { const int t = colt / split_cols; base += (size_t)t * split_stride; colt -= t * split_cols; }
;         const int col0 = colt + wc * 32 + 8 * fq;
; #pragma unroll
;         for (int ai = 0; ai < 2; ++ai)
; #pragma unroll
;             for (int m = 0; m < 4; ++m) { const int row = row0 + ai * HALF + m * 16;
;                 bf16_t* rowp = slot_stride ? base + (size_t)(colt >> 7) * slot_stride + (size_t)row * 128 + wc * 32 + 8 * fq : base + (size_t)row * ldc + col0;
; #pragma unroll
;                 for (int bj = 0; bj < 2; ++bj) { const f32x4 v0 = acc[ai][bj][m][0], v1 = acc[ai][bj][m][1];
;                     u32x4 w; w.x = pk_bf16(v0[0], v0[1]); w.y = pk_bf16(v0[2], v0[3]); w.z = pk_bf16(v1[0], v1[1]); w.w = pk_bf16(v1[2], v1[3]);
;                     *(u32x4*)(rowp + (slot_stride ? (size_t)bj * slot_stride : (size_t)bj * HALF)) = w; } }
; template <class Epi, class Sched>
; __device__ __forceinline__ void gemm_phase(LAS unsigned char* lds, const Gemm g, const Sched& S, const Epi& E) {
;     ...
;         E(acc, cur, wr, wc, fr, fq); S.done(cur);
;         if (!has_next) break;
; #pragma unroll
;         for (int a = 0; a < 2; ++a)
; #pragma unroll
;             for (int b = 0; b < 2; ++b)
; #pragma unroll
;                 for (int m = 0; m < 4; ++m)
; #pragma unroll
;                     for (int n = 0; n < 2; ++n) acc[a][b][m][n] = (f32x4){0.f, 0.f, 0.f, 0.f};
;         cur = nxt; cA = nA; cB = nB; ++ui;
;     }
;     PG8_WAIT_V(0);
;     if (wr == 0) PG8_BAR;
;     PG8_BAR;
	s_waitcnt lgkmcnt(0)
	v_lshl_add_u32 v156, s75, 8, v9
	s_lshl_b32 s1, s15, 1
	s_mul_i32 s15, s15, 0x1100000
	s_mul_hi_i32 s1, s1, 0x880000
	s_add_u32 s66, s82, s15
	v_ashrrev_i32_e32 v157, 31, v156
	s_addc_u32 s67, s83, s1
	v_lshlrev_b64 v[158:159], 8, v[156:157]
	v_lshl_add_u64 v[158:159], s[66:67], 0, v[158:159]
	v_lshl_add_u64 v[158:159], v[158:159], 0, s[2:3]
	v_mov_b32_e32 v153, v8
	v_lshl_add_u64 v[158:159], v[158:159], 0, v[152:153]
	v_cvt_pk_bf16_f32 v114, v114, v115
	v_cvt_pk_bf16_f32 v115, v116, v117
	v_cvt_pk_bf16_f32 v116, v106, v107
	v_add_co_u32_e32 v106, vcc, s87, v158
	v_cvt_pk_bf16_f32 v117, v108, v109
	s_nop 0
	v_addc_co_u32_e32 v107, vcc, 0, v159, vcc
	global_store_dwordx4 v[106:107], v[114:117], off
	v_or_b32_e32 v106, 16, v156
	v_ashrrev_i32_e32 v107, 31, v106
	v_lshlrev_b64 v[106:107], 8, v[106:107]
	v_lshl_add_u64 v[106:107], s[66:67], 0, v[106:107]
	v_lshl_add_u64 v[106:107], v[106:107], 0, s[2:3]
	v_lshl_add_u64 v[114:115], v[106:107], 0, v[152:153]
	v_cvt_pk_bf16_f32 v98, v98, v99
	v_cvt_pk_bf16_f32 v99, v100, v101
	v_cvt_pk_bf16_f32 v100, v90, v91
	v_add_co_u32_e32 v90, vcc, s87, v114
	v_cvt_pk_bf16_f32 v101, v92, v93
	s_nop 0
	v_addc_co_u32_e32 v91, vcc, 0, v115, vcc
	global_store_dwordx4 v[90:91], v[98:101], off
	v_or_b32_e32 v90, 32, v156
	v_ashrrev_i32_e32 v91, 31, v90
	v_lshlrev_b64 v[90:91], 8, v[90:91]
	v_lshl_add_u64 v[90:91], s[66:67], 0, v[90:91]
	v_lshl_add_u64 v[90:91], v[90:91], 0, s[2:3]
	v_lshl_add_u64 v[98:99], v[90:91], 0, v[152:153]
	v_cvt_pk_bf16_f32 v82, v82, v83
	v_cvt_pk_bf16_f32 v83, v84, v85
	v_cvt_pk_bf16_f32 v84, v74, v75
	v_add_co_u32_e32 v74, vcc, s87, v98
	v_cvt_pk_bf16_f32 v85, v76, v77
	s_nop 0
	v_addc_co_u32_e32 v75, vcc, 0, v99, vcc
	global_store_dwordx4 v[74:75], v[82:85], off
	v_or_b32_e32 v74, 48, v156
	v_ashrrev_i32_e32 v75, 31, v74
	v_lshlrev_b64 v[74:75], 8, v[74:75]
	v_lshl_add_u64 v[74:75], s[66:67], 0, v[74:75]
	v_lshl_add_u64 v[74:75], v[74:75], 0, s[2:3]
	v_lshl_add_u64 v[82:83], v[74:75], 0, v[152:153]
	v_cvt_pk_bf16_f32 v70, v70, v71
	v_cvt_pk_bf16_f32 v71, v72, v73
	v_cvt_pk_bf16_f32 v72, v66, v67
	v_add_co_u32_e32 v66, vcc, s87, v82
	s_mov_b32 s1, 0x9000
	s_nop 0
	v_addc_co_u32_e32 v67, vcc, 0, v83, vcc
	v_cvt_pk_bf16_f32 v62, v62, v63
	v_cvt_pk_bf16_f32 v63, v64, v65
	v_cvt_pk_bf16_f32 v64, v58, v59
	v_add_co_u32_e32 v58, vcc, s1, v158
	s_mov_b32 s1, 0x889000
	s_nop 0
	v_addc_co_u32_e32 v59, vcc, 0, v159, vcc
	v_cvt_pk_bf16_f32 v65, v60, v61
	v_add_co_u32_e32 v60, vcc, s1, v158
	v_cvt_pk_bf16_f32 v30, v30, v31
	s_nop 0
	v_addc_co_u32_e32 v61, vcc, 0, v159, vcc
	v_cvt_pk_bf16_f32 v31, v32, v33
	v_cvt_pk_bf16_f32 v32, v26, v27
	v_cvt_pk_bf16_f32 v33, v28, v29
	s_mov_b32 s1, 0xb000
	global_store_dwordx4 v[60:61], v[30:33], off
	v_cvt_pk_bf16_f32 v14, v14, v15
	v_cvt_pk_bf16_f32 v15, v16, v17
	v_add_co_u32_e32 v30, vcc, s1, v158
	s_mov_b32 s1, 0x88a000
	s_nop 0
	v_addc_co_u32_e32 v31, vcc, 0, v159, vcc
	v_cvt_pk_bf16_f32 v16, v10, v11
	v_add_co_u32_e32 v10, vcc, s1, v158
	v_cvt_pk_bf16_f32 v4, v4, v5
	s_nop 0
	v_addc_co_u32_e32 v11, vcc, 0, v159, vcc
	v_cvt_pk_bf16_f32 v5, v6, v7
	v_cvt_pk_bf16_f32 v6, v0, v1
	v_add_co_u32_e32 v0, vcc, 0x88b000, v158
	v_cvt_pk_bf16_f32 v17, v12, v13
	s_nop 0
	v_addc_co_u32_e32 v1, vcc, 0, v159, vcc
	v_cvt_pk_bf16_f32 v126, v126, v127
	v_cvt_pk_bf16_f32 v127, v128, v129
	v_cvt_pk_bf16_f32 v128, v122, v123
	v_cvt_pk_bf16_f32 v129, v124, v125
	v_cvt_pk_bf16_f32 v106, v118, v119
	v_cvt_pk_bf16_f32 v107, v120, v121
	v_cvt_pk_bf16_f32 v108, v110, v111
	v_cvt_pk_bf16_f32 v109, v112, v113
	v_cvt_pk_bf16_f32 v90, v102, v103
	v_cvt_pk_bf16_f32 v91, v104, v105
	v_cvt_pk_bf16_f32 v92, v94, v95
	v_cvt_pk_bf16_f32 v93, v96, v97
	v_cvt_pk_bf16_f32 v74, v86, v87
	v_cvt_pk_bf16_f32 v75, v88, v89
	v_cvt_pk_bf16_f32 v76, v78, v79
	v_cvt_pk_bf16_f32 v77, v80, v81
	v_cvt_pk_bf16_f32 v73, v68, v69
	v_cvt_pk_bf16_f32 v46, v46, v47
	v_cvt_pk_bf16_f32 v47, v48, v49
	v_cvt_pk_bf16_f32 v48, v42, v43
	v_cvt_pk_bf16_f32 v49, v44, v45
	v_cvt_pk_bf16_f32 v42, v54, v55
	v_cvt_pk_bf16_f32 v43, v56, v57
	v_cvt_pk_bf16_f32 v44, v50, v51
	v_cvt_pk_bf16_f32 v45, v52, v53
	v_cvt_pk_bf16_f32 v26, v38, v39
	v_cvt_pk_bf16_f32 v27, v40, v41
	v_cvt_pk_bf16_f32 v28, v34, v35
	v_cvt_pk_bf16_f32 v29, v36, v37
	global_store_dwordx4 v[10:11], v[14:17], off
	v_cvt_pk_bf16_f32 v10, v22, v23
	v_cvt_pk_bf16_f32 v11, v24, v25
	v_cvt_pk_bf16_f32 v12, v18, v19
	v_cvt_pk_bf16_f32 v13, v20, v21
	v_cvt_pk_bf16_f32 v7, v2, v3
	s_and_b64 vcc, exec, s[38:39]
	s_mov_b32 s15, s0
	s_mov_b32 s75, s40
	s_mov_b64 s[66:67], s[88:89]
	s_mov_b64 s[70:71], s[42:43]
	global_store_dwordx4 v[158:159], v[126:129], off
	global_store_dwordx4 v[114:115], v[106:109], off
	global_store_dwordx4 v[98:99], v[90:93], off
	global_store_dwordx4 v[82:83], v[74:77], off
	global_store_dwordx4 v[66:67], v[70:73], off
	global_store_dwordx4 v[58:59], v[62:65], off offset:-4096
	global_store_dwordx4 v[60:61], v[46:49], off offset:-4096
	global_store_dwordx4 v[58:59], v[42:45], off
	global_store_dwordx4 v[30:31], v[26:29], off offset:-4096
	global_store_dwordx4 v[30:31], v[10:13], off
	global_store_dwordx4 v[0:1], v[4:7], off
	s_cbranch_vccz .LBB0_184
	s_waitcnt vmcnt(0)
	v_readlane_b32 s14, v244, 49
	v_readlane_b32 s16, v244, 51
	v_readlane_b32 s70, v244, 55
	s_cmpk_gt_u32 s5, 0xff
	v_readlane_b32 s15, v244, 50
	v_readlane_b32 s17, v244, 52
	v_readlane_b32 s71, v244, 56
	s_cbranch_scc1 .LBB0_191
	s_barrier

; #define PG8_STAGE(bufoff, gbase, voff) do { _Pragma("unroll") for (int _i = 0; _i < 2; ++_i) \
;         __builtin_amdgcn_global_load_lds((const unsigned*)((const char*)(gbase) + (voff)[_i]), (LAS unsigned*)(lds + (bufoff) + ldsw + _i * 8192), 16, 0, 0); } while (0)
; #define PG8_LDA(dst, b, h) do { _Pragma("unroll") for (int m = 0; m < 4; ++m) _Pragma("unroll") for (int k = 0; k < 2; ++k) dst[m][k] = *(const LAS bf16x8*)(lds + PG8_SA(b, h) + aoff + m * 2048 + k * 1024); } while (0)
; #define PG8_LDB(dst, b, h) do { _Pragma("unroll") for (int n = 0; n < 2; ++n) _Pragma("unroll") for (int k = 0; k < 2; ++k) dst[n][k] = *(const LAS bf16x8*)(lds + PG8_SB(b, h) + boff + n * 2048 + k * 1024); } while (0)
; #define PG8_MMA(ai, bj, At, Bt) do { __builtin_amdgcn_s_setprio(1); _Pragma("unroll") for (int m = 0; m < 4; ++m) _Pragma("unroll") for (int n = 0; n < 2; ++n) _Pragma("unroll") for (int k = 0; k < 2; ++k) \
;         acc[ai][bj][m][n] = __builtin_amdgcn_mfma_f32_16x16x32_bf16(Bt[n][k], At[m][k], acc[ai][bj][m][n], 0, 0, 0); __builtin_amdgcn_s_setprio(0); } while (0)
; #define PG8_BAR __builtin_amdgcn_s_barrier()
; template <class Epi, class Sched>
; __device__ __forceinline__ void gemm_phase(LAS unsigned char* lds, const Gemm g, const Sched& S, const Epi& E) {
;     ...
;         const bool has_next = S.next(ui + 1, nxt);
;         const char* nA = has_next ? (const char*)g.A + (size_t)nxt.pm * tstep : cA; const char* nB = has_next ? (const char*)g.Bt + (size_t)nxt.pn * tstep : cB;
;         for (int t = 0; t < nt; t += 2) {
;             const bool last = (t == nt - 2);
;             const char* a1 = cA + (size_t)(t + 1) * kstep;
;             const char* a2 = last ? nA : cA + (size_t)(t + 2) * kstep; const char* b2 = last ? nB : cB + (size_t)(t + 2) * kstep;
;             const char* a3 = a2 + kstep; const char* b3 = b2 + kstep;
;             if (last && has_next) S.a_ready(nxt);
;             PG8_LDB(B0, 0, 0); PG8_SCHED; PG8_LDA(At, 0, 0); PG8_STAGE(PG8_SA(1, 1), a1 + hstep, voffA);
;             PG8_WAIT_L(8); PG8_BAR; PG8_WAIT_L(0); PG8_MMA(0, 0, At, B0); PG8_BAR; PG8_SCHED;
;             PG8_LDB(B1, 0, 1); PG8_STAGE(PG8_SB(0, 0), b2, voffB);
;             PG8_BAR; PG8_WAIT_L(0); PG8_MMA(0, 1, At, B1); PG8_BAR;
;             PG8_LDA(At, 0, 1); PG8_STAGE(PG8_SA(0, 0), a2, voffA);
;             PG8_BAR; PG8_WAIT_L(0); PG8_MMA(1, 0, At, B0); PG8_BAR; PG8_SCHED;
.LBB0_515:
	s_add_u32 s20, vcc_lo, 0xfffc0080
	s_addc_u32 s21, vcc_hi, -1
	s_add_i32 s22, 16, 0x10000
	v_add_u32_e32 v155, s22, v152
	s_cmp_eq_u32 s19, 12
	s_cselect_b32 s73, s89, s21
	s_cselect_b32 s72, s16, s20
	s_cselect_b32 s67, s17, s18
	s_cselect_b32 s66, s43, s74
	v_lshl_add_u64 v[216:217], vcc, 0, v[148:149]
	s_add_i32 m0, s1, 0xc000
	ds_read_b128 v[172:175], v154
	ds_read_b128 v[188:191], v154 offset:1024
	ds_read_b128 v[192:195], v154 offset:2048
	ds_read_b128 v[196:199], v154 offset:3072
	ds_read_b128 v[200:203], v154 offset:4096
	ds_read_b128 v[204:207], v154 offset:5120
	ds_read_b128 v[208:211], v154 offset:6144
	ds_read_b128 v[212:215], v154 offset:7168
	global_load_lds_dwordx4 v[216:217], off
	v_lshl_add_u64 v[216:217], vcc, 0, v[150:151]
	s_add_i32 m0, s1, 0xe000
	s_nop 0
	global_load_lds_dwordx4 v[216:217], off
	s_waitcnt lgkmcnt(8)
	s_barrier
	s_waitcnt lgkmcnt(0)
	s_setprio 1
	s_waitcnt lgkmcnt(0)
	v_mfma_f32_16x16x32_bf16 v[126:129], v[156:159], v[172:175], v[126:129]
	v_mfma_f32_16x16x32_bf16 v[122:125], v[164:167], v[172:175], v[122:125]
	v_mfma_f32_16x16x32_bf16 v[118:121], v[156:159], v[192:195], v[118:121]
	v_mfma_f32_16x16x32_bf16 v[114:117], v[164:167], v[192:195], v[114:117]
	v_mfma_f32_16x16x32_bf16 v[102:105], v[156:159], v[200:203], v[102:105]
	v_mfma_f32_16x16x32_bf16 v[98:101], v[164:167], v[200:203], v[98:101]
	v_mfma_f32_16x16x32_bf16 v[86:89], v[156:159], v[208:211], v[86:89]
	v_mfma_f32_16x16x32_bf16 v[82:85], v[164:167], v[208:211], v[82:85]
	v_mfma_f32_16x16x32_bf16 v[126:129], v[160:163], v[188:191], v[126:129]
	v_mfma_f32_16x16x32_bf16 v[122:125], v[168:171], v[188:191], v[122:125]
	v_mfma_f32_16x16x32_bf16 v[118:121], v[160:163], v[196:199], v[118:121]
	v_mfma_f32_16x16x32_bf16 v[114:117], v[168:171], v[196:199], v[114:117]
	v_mfma_f32_16x16x32_bf16 v[102:105], v[160:163], v[204:207], v[102:105]
	v_mfma_f32_16x16x32_bf16 v[98:101], v[168:171], v[204:207], v[98:101]
	v_mfma_f32_16x16x32_bf16 v[86:89], v[160:163], v[212:215], v[86:89]
	v_mfma_f32_16x16x32_bf16 v[82:85], v[168:171], v[212:215], v[82:85]
	s_setprio 0
	s_barrier
	s_add_i32 s23, 16, 0x14000
	s_add_i32 s20, s22, s9
	v_add_u32_e32 v155, s23, v152
	v_lshl_add_u64 v[232:233], s[66:67], 0, v[144:145]
	s_mov_b32 m0, s20
	ds_read_b128 v[216:219], v155
	ds_read_b128 v[220:223], v155 offset:1024
	ds_read_b128 v[224:227], v155 offset:2048
	ds_read_b128 v[228:231], v155 offset:3072
	global_load_lds_dwordx4 v[232:233], off
	v_lshl_add_u64 v[234:235], s[66:67], 0, v[140:141]
	s_add_i32 m0, s20, 0x2000
	s_nop 0
	global_load_lds_dwordx4 v[234:235], off
	s_barrier
	s_waitcnt lgkmcnt(0)
	s_setprio 1
	s_waitcnt lgkmcnt(0)
	v_mfma_f32_16x16x32_bf16 v[110:113], v[216:219], v[172:175], v[110:113]
	v_mfma_f32_16x16x32_bf16 v[106:109], v[224:227], v[172:175], v[106:109]
	v_mfma_f32_16x16x32_bf16 v[94:97], v[216:219], v[192:195], v[94:97]
	v_mfma_f32_16x16x32_bf16 v[90:93], v[224:227], v[192:195], v[90:93]
	v_mfma_f32_16x16x32_bf16 v[78:81], v[216:219], v[200:203], v[78:81]
	v_mfma_f32_16x16x32_bf16 v[74:77], v[224:227], v[200:203], v[74:77]
	v_mfma_f32_16x16x32_bf16 v[70:73], v[216:219], v[208:211], v[70:73]
	v_mfma_f32_16x16x32_bf16 v[66:69], v[224:227], v[208:211], v[66:69]
	v_mfma_f32_16x16x32_bf16 v[110:113], v[220:223], v[188:191], v[110:113]
	v_mfma_f32_16x16x32_bf16 v[106:109], v[228:231], v[188:191], v[106:109]
	v_mfma_f32_16x16x32_bf16 v[94:97], v[220:223], v[196:199], v[94:97]
	v_mfma_f32_16x16x32_bf16 v[90:93], v[228:231], v[196:199], v[90:93]
	v_mfma_f32_16x16x32_bf16 v[78:81], v[220:223], v[204:207], v[78:81]
	v_mfma_f32_16x16x32_bf16 v[74:77], v[228:231], v[204:207], v[74:77]
	v_mfma_f32_16x16x32_bf16 v[70:73], v[220:223], v[212:215], v[70:73]
	v_mfma_f32_16x16x32_bf16 v[66:69], v[228:231], v[212:215], v[66:69]
	s_setprio 0
	s_mov_b32 m0, s1
	v_lshl_add_u64 v[236:237], s[72:73], 0, v[146:147]
	s_barrier
	ds_read_b128 v[172:175], v154 offset:16384
	ds_read_b128 v[188:191], v154 offset:17408
	ds_read_b128 v[192:195], v154 offset:18432
	ds_read_b128 v[196:199], v154 offset:19456
	ds_read_b128 v[200:203], v154 offset:20480
	ds_read_b128 v[204:207], v154 offset:21504
	ds_read_b128 v[208:211], v154 offset:22528
	ds_read_b128 v[212:215], v154 offset:23552
	global_load_lds_dwordx4 v[236:237], off
	v_lshl_add_u64 v[238:239], s[72:73], 0, v[142:143]
	s_mov_b32 m0, s11
	s_nop 0
	global_load_lds_dwordx4 v[238:239], off
	s_barrier
	s_waitcnt lgkmcnt(0)
	s_setprio 1
	s_waitcnt lgkmcnt(0)
	v_mfma_f32_16x16x32_bf16 v[62:65], v[156:159], v[172:175], v[62:65]
	v_mfma_f32_16x16x32_bf16 v[58:61], v[164:167], v[172:175], v[58:61]
	v_mfma_f32_16x16x32_bf16 v[54:57], v[156:159], v[192:195], v[54:57]
	v_mfma_f32_16x16x32_bf16 v[50:53], v[164:167], v[192:195], v[50:53]
	v_mfma_f32_16x16x32_bf16 v[38:41], v[156:159], v[200:203], v[38:41]
	v_mfma_f32_16x16x32_bf16 v[34:37], v[164:167], v[200:203], v[34:37]
	v_mfma_f32_16x16x32_bf16 v[22:25], v[156:159], v[208:211], v[22:25]
	v_mfma_f32_16x16x32_bf16 v[18:21], v[164:167], v[208:211], v[18:21]
	v_mfma_f32_16x16x32_bf16 v[62:65], v[160:163], v[188:191], v[62:65]
	v_mfma_f32_16x16x32_bf16 v[58:61], v[168:171], v[188:191], v[58:61]
	v_mfma_f32_16x16x32_bf16 v[54:57], v[160:163], v[196:199], v[54:57]
	v_mfma_f32_16x16x32_bf16 v[50:53], v[168:171], v[196:199], v[50:53]
	v_mfma_f32_16x16x32_bf16 v[38:41], v[160:163], v[204:207], v[38:41]
	v_mfma_f32_16x16x32_bf16 v[34:37], v[168:171], v[204:207], v[34:37]
	v_mfma_f32_16x16x32_bf16 v[22:25], v[160:163], v[212:215], v[22:25]
	v_mfma_f32_16x16x32_bf16 v[18:21], v[168:171], v[212:215], v[18:21]
	s_setprio 0
	s_barrier
; #define PG8_STAGE(bufoff, gbase, voff) do { _Pragma("unroll") for (int _i = 0; _i < 2; ++_i) \
;         __builtin_amdgcn_global_load_lds((const unsigned*)((const char*)(gbase) + (voff)[_i]), (LAS unsigned*)(lds + (bufoff) + ldsw + _i * 8192), 16, 0, 0); } while (0)
; #define PG8_LDA(dst, b, h) do { _Pragma("unroll") for (int m = 0; m < 4; ++m) _Pragma("unroll") for (int k = 0; k < 2; ++k) dst[m][k] = *(const LAS bf16x8*)(lds + PG8_SA(b, h) + aoff + m * 2048 + k * 1024); } while (0)
; #define PG8_LDB(dst, b, h) do { _Pragma("unroll") for (int n = 0; n < 2; ++n) _Pragma("unroll") for (int k = 0; k < 2; ++k) dst[n][k] = *(const LAS bf16x8*)(lds + PG8_SB(b, h) + boff + n * 2048 + k * 1024); } while (0)
; #define PG8_MMA(ai, bj, At, Bt) do { __builtin_amdgcn_s_setprio(1); _Pragma("unroll") for (int m = 0; m < 4; ++m) _Pragma("unroll") for (int n = 0; n < 2; ++n) _Pragma("unroll") for (int k = 0; k < 2; ++k) \
;         acc[ai][bj][m][n] = __builtin_amdgcn_mfma_f32_16x16x32_bf16(Bt[n][k], At[m][k], acc[ai][bj][m][n], 0, 0, 0); __builtin_amdgcn_s_setprio(0); } while (0)
; #define PG8_WAIT_V(n) asm volatile("s_waitcnt vmcnt(" #n ")" ::: "memory")
; #define PG8_WAIT_L(n) asm volatile("s_waitcnt lgkmcnt(" #n ")" ::: "memory")
; #define PG8_BAR __builtin_amdgcn_s_barrier()
; #define PG8_SCHED __builtin_amdgcn_sched_barrier(0)
; template <class Epi, class Sched>
; __device__ __forceinline__ void gemm_phase(LAS unsigned char* lds, const Gemm g, const Sched& S, const Epi& E) {
;     ...
;             PG8_STAGE(PG8_SB(0, 1), b2 + hstep, voffB);
;             PG8_WAIT_V(6); PG8_BAR; PG8_MMA(1, 1, At, B1); PG8_BAR;
;             PG8_LDB(B0, 1, 0); PG8_SCHED; PG8_LDA(At, 1, 0); PG8_STAGE(PG8_SA(0, 1), a2 + hstep, voffA);
;             PG8_WAIT_L(8); PG8_BAR; PG8_WAIT_L(0); PG8_MMA(0, 0, At, B0); PG8_BAR; PG8_SCHED;
;             PG8_LDB(B1, 1, 1); PG8_STAGE(PG8_SB(1, 0), b3, voffB);
;             PG8_BAR; PG8_WAIT_L(0); PG8_MMA(0, 1, At, B1); PG8_BAR;
;             PG8_LDA(At, 1, 1); PG8_STAGE(PG8_SA(1, 0), a3, voffA);
;             PG8_BAR; PG8_WAIT_L(0); PG8_MMA(1, 0, At, B0); PG8_BAR; PG8_SCHED;
	s_add_u32 s20, s66, 0x40000
	s_addc_u32 s21, s67, 0
	s_add_i32 s22, s23, s9
	v_lshl_add_u64 v[156:157], s[20:21], 0, v[144:145]
	s_mov_b32 m0, s22
	s_nop 0
	global_load_lds_dwordx4 v[156:157], off
	v_lshl_add_u64 v[156:157], s[20:21], 0, v[140:141]
	s_add_i32 m0, s22, 0x2000
	s_nop 0
	global_load_lds_dwordx4 v[156:157], off
	s_waitcnt vmcnt(6)
	s_barrier
	s_setprio 1
	v_mfma_f32_16x16x32_bf16 v[46:49], v[216:219], v[172:175], v[46:49]
	v_add_u32_e32 v155, 0x18010, v152
	v_mfma_f32_16x16x32_bf16 v[42:45], v[224:227], v[172:175], v[42:45]
	ds_read_b128 v[156:159], v155
	v_mfma_f32_16x16x32_bf16 v[30:33], v[216:219], v[192:195], v[30:33]
	ds_read_b128 v[160:163], v155 offset:1024
	v_mfma_f32_16x16x32_bf16 v[26:29], v[224:227], v[192:195], v[26:29]
	ds_read_b128 v[164:167], v155 offset:2048
	v_mfma_f32_16x16x32_bf16 v[14:17], v[216:219], v[200:203], v[14:17]
	ds_read_b128 v[168:171], v155 offset:3072
	v_mfma_f32_16x16x32_bf16 v[10:13], v[224:227], v[200:203], v[10:13]
	v_mfma_f32_16x16x32_bf16 v[4:7], v[216:219], v[208:211], v[4:7]
	v_mfma_f32_16x16x32_bf16 v[0:3], v[224:227], v[208:211], v[0:3]
	v_mfma_f32_16x16x32_bf16 v[46:49], v[220:223], v[188:191], v[46:49]
	v_mfma_f32_16x16x32_bf16 v[42:45], v[228:231], v[188:191], v[42:45]
	v_mfma_f32_16x16x32_bf16 v[30:33], v[220:223], v[196:199], v[30:33]
	v_mfma_f32_16x16x32_bf16 v[26:29], v[228:231], v[196:199], v[26:29]
	v_mfma_f32_16x16x32_bf16 v[14:17], v[220:223], v[204:207], v[14:17]
	v_mfma_f32_16x16x32_bf16 v[10:13], v[228:231], v[204:207], v[10:13]
	v_mfma_f32_16x16x32_bf16 v[4:7], v[220:223], v[212:215], v[4:7]
	v_mfma_f32_16x16x32_bf16 v[0:3], v[228:231], v[212:215], v[0:3]
	s_setprio 0
	s_add_i32 s22, 16, 0x18000
	v_add_u32_e32 v155, s22, v152
	s_barrier
	s_add_u32 s20, s72, 0x40000
	s_addc_u32 s21, s73, 0
	s_mov_b32 m0, s41
	v_lshl_add_u64 v[216:217], s[20:21], 0, v[146:147]
	ds_read_b128 v[172:175], v154 offset:32768
	ds_read_b128 v[188:191], v154 offset:33792
	ds_read_b128 v[192:195], v154 offset:34816
	ds_read_b128 v[196:199], v154 offset:35840
	ds_read_b128 v[200:203], v154 offset:36864
	ds_read_b128 v[204:207], v154 offset:37888
	ds_read_b128 v[208:211], v154 offset:38912
	ds_read_b128 v[212:215], v154 offset:39936
	global_load_lds_dwordx4 v[216:217], off
	v_lshl_add_u64 v[216:217], s[20:21], 0, v[142:143]
	s_mov_b32 m0, s12
	s_nop 0
	global_load_lds_dwordx4 v[216:217], off
	s_waitcnt lgkmcnt(8)
	s_barrier
	s_waitcnt lgkmcnt(0)
	s_setprio 1
	s_waitcnt lgkmcnt(0)
	v_mfma_f32_16x16x32_bf16 v[126:129], v[156:159], v[172:175], v[126:129]
	v_mfma_f32_16x16x32_bf16 v[122:125], v[164:167], v[172:175], v[122:125]
	v_mfma_f32_16x16x32_bf16 v[118:121], v[156:159], v[192:195], v[118:121]
	v_mfma_f32_16x16x32_bf16 v[114:117], v[164:167], v[192:195], v[114:117]
	v_mfma_f32_16x16x32_bf16 v[102:105], v[156:159], v[200:203], v[102:105]
	v_mfma_f32_16x16x32_bf16 v[98:101], v[164:167], v[200:203], v[98:101]
	v_mfma_f32_16x16x32_bf16 v[86:89], v[156:159], v[208:211], v[86:89]
	v_mfma_f32_16x16x32_bf16 v[82:85], v[164:167], v[208:211], v[82:85]
	v_mfma_f32_16x16x32_bf16 v[126:129], v[160:163], v[188:191], v[126:129]
	v_mfma_f32_16x16x32_bf16 v[122:125], v[168:171], v[188:191], v[122:125]
	v_mfma_f32_16x16x32_bf16 v[118:121], v[160:163], v[196:199], v[118:121]
	v_mfma_f32_16x16x32_bf16 v[114:117], v[168:171], v[196:199], v[114:117]
	v_mfma_f32_16x16x32_bf16 v[102:105], v[160:163], v[204:207], v[102:105]
	v_mfma_f32_16x16x32_bf16 v[98:101], v[168:171], v[204:207], v[98:101]
	v_mfma_f32_16x16x32_bf16 v[86:89], v[160:163], v[212:215], v[86:89]
	v_mfma_f32_16x16x32_bf16 v[82:85], v[168:171], v[212:215], v[82:85]
	s_setprio 0
	s_barrier
	s_add_i32 s23, 16, 0x1c000
	s_add_i32 s20, s22, s9
	v_add_u32_e32 v155, s23, v152
	v_lshl_add_u64 v[232:233], v[232:233], 0, s[94:95]
	s_mov_b32 m0, s20
	ds_read_b128 v[216:219], v155
	ds_read_b128 v[220:223], v155 offset:1024
	ds_read_b128 v[224:227], v155 offset:2048
	ds_read_b128 v[228:231], v155 offset:3072
	global_load_lds_dwordx4 v[232:233], off
	v_lshl_add_u64 v[232:233], v[234:235], 0, s[94:95]
	s_add_i32 m0, s20, 0x2000
	s_nop 0
	global_load_lds_dwordx4 v[232:233], off
	s_barrier
	s_waitcnt lgkmcnt(0)
	s_setprio 1
	s_waitcnt lgkmcnt(0)
	v_mfma_f32_16x16x32_bf16 v[110:113], v[216:219], v[172:175], v[110:113]
	v_mfma_f32_16x16x32_bf16 v[106:109], v[224:227], v[172:175], v[106:109]
	v_mfma_f32_16x16x32_bf16 v[94:97], v[216:219], v[192:195], v[94:97]
	v_mfma_f32_16x16x32_bf16 v[90:93], v[224:227], v[192:195], v[90:93]
	v_mfma_f32_16x16x32_bf16 v[78:81], v[216:219], v[200:203], v[78:81]
	v_mfma_f32_16x16x32_bf16 v[74:77], v[224:227], v[200:203], v[74:77]
	v_mfma_f32_16x16x32_bf16 v[70:73], v[216:219], v[208:211], v[70:73]
	v_mfma_f32_16x16x32_bf16 v[66:69], v[224:227], v[208:211], v[66:69]
	v_mfma_f32_16x16x32_bf16 v[110:113], v[220:223], v[188:191], v[110:113]
	v_mfma_f32_16x16x32_bf16 v[106:109], v[228:231], v[188:191], v[106:109]
	v_mfma_f32_16x16x32_bf16 v[94:97], v[220:223], v[196:199], v[94:97]
	v_mfma_f32_16x16x32_bf16 v[90:93], v[228:231], v[196:199], v[90:93]
	v_mfma_f32_16x16x32_bf16 v[78:81], v[220:223], v[204:207], v[78:81]
	v_mfma_f32_16x16x32_bf16 v[74:77], v[228:231], v[204:207], v[74:77]
	v_mfma_f32_16x16x32_bf16 v[70:73], v[220:223], v[212:215], v[70:73]
	v_mfma_f32_16x16x32_bf16 v[66:69], v[228:231], v[212:215], v[66:69]
	s_setprio 0
	s_mov_b32 m0, s13
	v_lshl_add_u64 v[232:233], v[236:237], 0, s[94:95]
	s_barrier
; #define PG8_STAGE(bufoff, gbase, voff) do { _Pragma("unroll") for (int _i = 0; _i < 2; ++_i) \
;         __builtin_amdgcn_global_load_lds((const unsigned*)((const char*)(gbase) + (voff)[_i]), (LAS unsigned*)(lds + (bufoff) + ldsw + _i * 8192), 16, 0, 0); } while (0)
; #define PG8_LDA(dst, b, h) do { _Pragma("unroll") for (int m = 0; m < 4; ++m) _Pragma("unroll") for (int k = 0; k < 2; ++k) dst[m][k] = *(const LAS bf16x8*)(lds + PG8_SA(b, h) + aoff + m * 2048 + k * 1024); } while (0)
; #define PG8_LDB(dst, b, h) do { _Pragma("unroll") for (int n = 0; n < 2; ++n) _Pragma("unroll") for (int k = 0; k < 2; ++k) dst[n][k] = *(const LAS bf16x8*)(lds + PG8_SB(b, h) + boff + n * 2048 + k * 1024); } while (0)
; #define PG8_MMA(ai, bj, At, Bt) do { __builtin_amdgcn_s_setprio(1); _Pragma("unroll") for (int m = 0; m < 4; ++m) _Pragma("unroll") for (int n = 0; n < 2; ++n) _Pragma("unroll") for (int k = 0; k < 2; ++k) \
;         acc[ai][bj][m][n] = __builtin_amdgcn_mfma_f32_16x16x32_bf16(Bt[n][k], At[m][k], acc[ai][bj][m][n], 0, 0, 0); __builtin_amdgcn_s_setprio(0); } while (0)
; #define PG8_WAIT_V(n) asm volatile("s_waitcnt vmcnt(" #n ")" ::: "memory")
; #define PG8_WAIT_L(n) asm volatile("s_waitcnt lgkmcnt(" #n ")" ::: "memory")
; #define PG8_BAR __builtin_amdgcn_s_barrier()
; #define PG8_SCHED __builtin_amdgcn_sched_barrier(0)
; template <class Epi, class Sched>
; __device__ __forceinline__ void gemm_phase(LAS unsigned char* lds, const Gemm g, const Sched& S, const Epi& E) {
;     ...
;             PG8_LDB(B0, 0, 0); PG8_SCHED; PG8_LDA(At, 0, 0); PG8_STAGE(PG8_SA(1, 1), a1 + hstep, voffA);
;     ...
;             PG8_LDA(At, 1, 1); PG8_STAGE(PG8_SA(1, 0), a3, voffA);
;             PG8_BAR; PG8_WAIT_L(0); PG8_MMA(1, 0, At, B0); PG8_BAR; PG8_SCHED;
;             PG8_STAGE(PG8_SB(1, 1), b3 + hstep, voffB);
;             PG8_WAIT_V(6); PG8_BAR; PG8_MMA(1, 1, At, B1); PG8_BAR;
;         }
	ds_read_b128 v[172:175], v154 offset:49152
	ds_read_b128 v[188:191], v154 offset:50176
	ds_read_b128 v[192:195], v154 offset:51200
	ds_read_b128 v[196:199], v154 offset:52224
	ds_read_b128 v[200:203], v154 offset:53248
	ds_read_b128 v[204:207], v154 offset:54272
	ds_read_b128 v[208:211], v154 offset:55296
	ds_read_b128 v[212:215], v154 offset:56320
	global_load_lds_dwordx4 v[232:233], off
	v_lshl_add_u64 v[232:233], v[238:239], 0, s[94:95]
	s_mov_b32 m0, s14
	s_nop 0
	global_load_lds_dwordx4 v[232:233], off
	s_barrier
	s_waitcnt lgkmcnt(0)
	s_setprio 1
	s_waitcnt lgkmcnt(0)
	v_mfma_f32_16x16x32_bf16 v[62:65], v[156:159], v[172:175], v[62:65]
	v_mfma_f32_16x16x32_bf16 v[58:61], v[164:167], v[172:175], v[58:61]
	v_mfma_f32_16x16x32_bf16 v[54:57], v[156:159], v[192:195], v[54:57]
	v_mfma_f32_16x16x32_bf16 v[50:53], v[164:167], v[192:195], v[50:53]
	v_mfma_f32_16x16x32_bf16 v[38:41], v[156:159], v[200:203], v[38:41]
	v_mfma_f32_16x16x32_bf16 v[34:37], v[164:167], v[200:203], v[34:37]
	v_mfma_f32_16x16x32_bf16 v[22:25], v[156:159], v[208:211], v[22:25]
	v_mfma_f32_16x16x32_bf16 v[18:21], v[164:167], v[208:211], v[18:21]
	v_mfma_f32_16x16x32_bf16 v[62:65], v[160:163], v[188:191], v[62:65]
	v_mfma_f32_16x16x32_bf16 v[58:61], v[168:171], v[188:191], v[58:61]
	v_mfma_f32_16x16x32_bf16 v[54:57], v[160:163], v[196:199], v[54:57]
	v_mfma_f32_16x16x32_bf16 v[50:53], v[168:171], v[196:199], v[50:53]
	v_mfma_f32_16x16x32_bf16 v[38:41], v[160:163], v[204:207], v[38:41]
	v_mfma_f32_16x16x32_bf16 v[34:37], v[168:171], v[204:207], v[34:37]
	v_mfma_f32_16x16x32_bf16 v[22:25], v[160:163], v[212:215], v[22:25]
	v_mfma_f32_16x16x32_bf16 v[18:21], v[168:171], v[212:215], v[18:21]
	s_setprio 0
	s_barrier
	s_add_u32 s20, s66, 0x40080
	s_addc_u32 s21, s67, 0
	s_add_i32 s22, s23, s9
	v_lshl_add_u64 v[156:157], s[20:21], 0, v[144:145]
	s_mov_b32 m0, s22
	s_nop 0
	global_load_lds_dwordx4 v[156:157], off
	v_lshl_add_u64 v[156:157], s[20:21], 0, v[140:141]
	s_add_i32 m0, s22, 0x2000
	s_nop 0
	global_load_lds_dwordx4 v[156:157], off
	s_waitcnt vmcnt(6)
	s_barrier
	s_setprio 1
	v_mfma_f32_16x16x32_bf16 v[46:49], v[216:219], v[172:175], v[46:49]
	v_add_u32_e32 v155, 0x10010, v152
	v_mfma_f32_16x16x32_bf16 v[42:45], v[224:227], v[172:175], v[42:45]
	ds_read_b128 v[156:159], v155
	v_mfma_f32_16x16x32_bf16 v[30:33], v[216:219], v[192:195], v[30:33]
	ds_read_b128 v[160:163], v155 offset:1024
	v_mfma_f32_16x16x32_bf16 v[26:29], v[224:227], v[192:195], v[26:29]
	ds_read_b128 v[164:167], v155 offset:2048
	v_mfma_f32_16x16x32_bf16 v[14:17], v[216:219], v[200:203], v[14:17]
	ds_read_b128 v[168:171], v155 offset:3072
	v_mfma_f32_16x16x32_bf16 v[10:13], v[224:227], v[200:203], v[10:13]
	v_mfma_f32_16x16x32_bf16 v[4:7], v[216:219], v[208:211], v[4:7]
	v_mfma_f32_16x16x32_bf16 v[0:3], v[224:227], v[208:211], v[0:3]
	v_mfma_f32_16x16x32_bf16 v[46:49], v[220:223], v[188:191], v[46:49]
	v_mfma_f32_16x16x32_bf16 v[42:45], v[228:231], v[188:191], v[42:45]
	v_mfma_f32_16x16x32_bf16 v[30:33], v[220:223], v[196:199], v[30:33]
	v_mfma_f32_16x16x32_bf16 v[26:29], v[228:231], v[196:199], v[26:29]
	v_mfma_f32_16x16x32_bf16 v[14:17], v[220:223], v[204:207], v[14:17]
	v_mfma_f32_16x16x32_bf16 v[10:13], v[228:231], v[204:207], v[10:13]
	v_mfma_f32_16x16x32_bf16 v[4:7], v[220:223], v[212:215], v[4:7]
	v_mfma_f32_16x16x32_bf16 v[0:3], v[228:231], v[212:215], v[0:3]
	s_setprio 0
	s_add_i32 s19, s19, 2
	s_add_u32 vcc_lo, vcc_lo, 0x100
	s_addc_u32 vcc_hi, vcc_hi, 0
	s_add_u32 s74, s74, 0x100
	s_addc_u32 s18, s18, 0
	s_cmp_gt_u32 s19, 13
	s_barrier
	s_cbranch_scc0 .LBB0_515
; __device__ __forceinline__ unsigned pk_bf16(float a, float b) { f32x2 v = {a, b}; bf2_t r = __builtin_convertvector(v, bf2_t); return __builtin_bit_cast(unsigned, r); }
; #define PG8_WAIT_V(n) asm volatile("s_waitcnt vmcnt(" #n ")" ::: "memory")
; #define PG8_BAR __builtin_amdgcn_s_barrier()
;     __device__ __forceinline__ void operator()(const f32x4 (&acc)[2][2][4][2], const Unit& u, int wr, int wc, int fr, int fq) const {
;         const int row0 = u.pm * BM + wr * 64 + fr; int colt = u.pn * BM; bf16_t* base = O;
;         if (split_cols) { const int t = colt / split_cols; base += (size_t)t * split_stride; colt -= t * split_cols; }
;         const int col0 = colt + wc * 32 + 8 * fq;
; #pragma unroll
;         for (int ai = 0; ai < 2; ++ai)
; #pragma unroll
;             for (int m = 0; m < 4; ++m) { const int row = row0 + ai * HALF + m * 16;
;                 bf16_t* rowp = slot_stride ? base + (size_t)(colt >> 7) * slot_stride + (size_t)row * 128 + wc * 32 + 8 * fq : base + (size_t)row * ldc + col0;
; #pragma unroll
;                 for (int bj = 0; bj < 2; ++bj) { const f32x4 v0 = acc[ai][bj][m][0], v1 = acc[ai][bj][m][1];
;                     u32x4 w; w.x = pk_bf16(v0[0], v0[1]); w.y = pk_bf16(v0[2], v0[3]); w.z = pk_bf16(v1[0], v1[1]); w.w = pk_bf16(v1[2], v1[3]);
;                     *(u32x4*)(rowp + (slot_stride ? (size_t)bj * slot_stride : (size_t)bj * HALF)) = w; } }
; template <class Epi, class Sched>
; __device__ __forceinline__ void gemm_phase(LAS unsigned char* lds, const Gemm g, const Sched& S, const Epi& E) {
;     ...
;         E(acc, cur, wr, wc, fr, fq); S.done(cur);
;         if (!has_next) break;
; #pragma unroll
;         for (int a = 0; a < 2; ++a)
; #pragma unroll
;             for (int b = 0; b < 2; ++b)
; #pragma unroll
;                 for (int m = 0; m < 4; ++m)
; #pragma unroll
;                     for (int n = 0; n < 2; ++n) acc[a][b][m][n] = (f32x4){0.f, 0.f, 0.f, 0.f};
;         cur = nxt; cA = nA; cB = nB; ++ui;
;     }
;     PG8_WAIT_V(0);
;     if (wr == 0) PG8_BAR;
;     PG8_BAR;
	s_waitcnt lgkmcnt(0)
	v_lshl_add_u32 v156, s40, 8, v9
	v_lshl_or_b32 v158, s0, 8, v153
	v_ashrrev_i32_e32 v159, 31, v158
	v_ashrrev_i32_e32 v157, 31, v156
	v_lshl_add_u64 v[158:159], v[158:159], 1, s[82:83]
	v_lshlrev_b64 v[160:161], 11, v[156:157]
	v_lshl_add_u64 v[160:161], v[158:159], 0, v[160:161]
	s_mov_b32 s0, 0x40000
	s_mov_b64 s[16:17], 0x40000
	v_cvt_pk_bf16_f32 v62, v62, v63
	v_cvt_pk_bf16_f32 v63, v64, v65
	v_cvt_pk_bf16_f32 v64, v58, v59
	v_add_co_u32_e32 v58, vcc, s0, v160
	v_cvt_pk_bf16_f32 v70, v70, v71
	v_cvt_pk_bf16_f32 v71, v72, v73
	v_cvt_pk_bf16_f32 v72, v66, v67
	v_lshl_add_u64 v[66:67], v[160:161], 0, s[16:17]
	v_addc_co_u32_e32 v59, vcc, 0, v161, vcc
	v_cvt_pk_bf16_f32 v46, v46, v47
	v_cvt_pk_bf16_f32 v47, v48, v49
	v_cvt_pk_bf16_f32 v48, v42, v43
	v_cvt_pk_bf16_f32 v49, v44, v45
	s_mov_b32 s0, 0x48000
	global_store_dwordx4 v[66:67], v[46:49], off offset:256
	s_mov_b64 s[16:17], 0x48000
	v_cvt_pk_bf16_f32 v110, v110, v111
	v_add_co_u32_e32 v48, vcc, s0, v160
	v_cvt_pk_bf16_f32 v111, v112, v113
	v_cvt_pk_bf16_f32 v112, v106, v107
	v_or_b32_e32 v106, 16, v156
	v_lshl_add_u64 v[46:47], v[160:161], 0, s[16:17]
	v_addc_co_u32_e32 v49, vcc, 0, v161, vcc
	v_cvt_pk_bf16_f32 v30, v30, v31
	v_cvt_pk_bf16_f32 v31, v32, v33
	v_cvt_pk_bf16_f32 v32, v26, v27
	v_cvt_pk_bf16_f32 v33, v28, v29
	s_mov_b32 s0, 0x50000
	v_ashrrev_i32_e32 v107, 31, v106
	v_cvt_pk_bf16_f32 v94, v94, v95
	v_cvt_pk_bf16_f32 v95, v96, v97
	v_cvt_pk_bf16_f32 v96, v90, v91
	v_or_b32_e32 v90, 32, v156
	global_store_dwordx4 v[46:47], v[30:33], off offset:256
	s_mov_b64 s[16:17], 0x50000
	v_cvt_pk_bf16_f32 v113, v108, v109
	v_add_co_u32_e32 v32, vcc, s0, v160
	v_lshlrev_b64 v[106:107], 11, v[106:107]
	v_ashrrev_i32_e32 v91, 31, v90
	v_cvt_pk_bf16_f32 v78, v78, v79
	v_cvt_pk_bf16_f32 v79, v80, v81
	v_cvt_pk_bf16_f32 v80, v74, v75
	v_or_b32_e32 v74, 48, v156
	v_lshl_add_u64 v[30:31], v[160:161], 0, s[16:17]
	v_addc_co_u32_e32 v33, vcc, 0, v161, vcc
	v_cvt_pk_bf16_f32 v14, v14, v15
	v_cvt_pk_bf16_f32 v15, v16, v17
	v_cvt_pk_bf16_f32 v16, v10, v11
	v_cvt_pk_bf16_f32 v17, v12, v13
	s_mov_b32 s0, 0x58000
	global_store_dwordx4 v[160:161], v[110:113], off offset:256
	v_cvt_pk_bf16_f32 v97, v92, v93
	v_lshlrev_b64 v[90:91], 11, v[90:91]
	v_lshl_add_u64 v[110:111], v[158:159], 0, v[106:107]
	v_ashrrev_i32_e32 v75, 31, v74
	global_store_dwordx4 v[30:31], v[14:17], off offset:256
	global_store_dwordx4 v[110:111], v[94:97], off offset:256
	v_cvt_pk_bf16_f32 v81, v76, v77
	v_add_co_u32_e32 v16, vcc, s0, v160
	v_lshl_add_u64 v[94:95], v[158:159], 0, v[90:91]
	v_lshlrev_b64 v[74:75], 11, v[74:75]
	s_mov_b64 s[16:17], 0x58000
	v_addc_co_u32_e32 v17, vcc, 0, v161, vcc
	v_cvt_pk_bf16_f32 v126, v126, v127
	v_cvt_pk_bf16_f32 v127, v128, v129
	v_cvt_pk_bf16_f32 v128, v122, v123
	v_cvt_pk_bf16_f32 v129, v124, v125
	v_cvt_pk_bf16_f32 v106, v118, v119
	v_cvt_pk_bf16_f32 v107, v120, v121
	v_cvt_pk_bf16_f32 v108, v114, v115
	v_cvt_pk_bf16_f32 v109, v116, v117
	v_cvt_pk_bf16_f32 v90, v102, v103
	v_cvt_pk_bf16_f32 v91, v104, v105
	v_cvt_pk_bf16_f32 v92, v98, v99
	v_cvt_pk_bf16_f32 v93, v100, v101
	global_store_dwordx4 v[94:95], v[78:81], off offset:256
	v_cvt_pk_bf16_f32 v76, v82, v83
	v_cvt_pk_bf16_f32 v77, v84, v85
	v_lshl_add_u64 v[78:79], v[158:159], 0, v[74:75]
	v_cvt_pk_bf16_f32 v74, v86, v87
	v_cvt_pk_bf16_f32 v75, v88, v89
	v_cvt_pk_bf16_f32 v73, v68, v69
	v_cvt_pk_bf16_f32 v65, v60, v61
	v_cvt_pk_bf16_f32 v42, v54, v55
	v_cvt_pk_bf16_f32 v43, v56, v57
	v_cvt_pk_bf16_f32 v44, v50, v51
	v_cvt_pk_bf16_f32 v45, v52, v53
	v_cvt_pk_bf16_f32 v26, v38, v39
	v_cvt_pk_bf16_f32 v27, v40, v41
	v_cvt_pk_bf16_f32 v28, v34, v35
	v_cvt_pk_bf16_f32 v29, v36, v37
	v_lshl_add_u64 v[14:15], v[160:161], 0, s[16:17]
	v_cvt_pk_bf16_f32 v10, v22, v23
	v_cvt_pk_bf16_f32 v11, v24, v25
	v_cvt_pk_bf16_f32 v12, v18, v19
	v_cvt_pk_bf16_f32 v13, v20, v21
	v_cvt_pk_bf16_f32 v4, v4, v5
	v_cvt_pk_bf16_f32 v5, v6, v7
	v_cvt_pk_bf16_f32 v6, v0, v1
	v_cvt_pk_bf16_f32 v7, v2, v3
	s_and_b64 vcc, exec, s[38:39]
	s_mov_b32 s0, s42
	s_mov_b32 s40, s88
	s_mov_b64 s[74:75], s[70:71]
	s_mov_b64 s[72:73], s[78:79]
	global_store_dwordx4 v[160:161], v[126:129], off
	global_store_dwordx4 v[110:111], v[106:109], off
	global_store_dwordx4 v[94:95], v[90:93], off
	global_store_dwordx4 v[78:79], v[74:77], off
	global_store_dwordx4 v[78:79], v[70:73], off offset:256
	global_store_dwordx4 v[58:59], v[62:65], off
	global_store_dwordx4 v[48:49], v[42:45], off
	global_store_dwordx4 v[32:33], v[26:29], off
	global_store_dwordx4 v[16:17], v[10:13], off
	global_store_dwordx4 v[14:15], v[4:7], off offset:256
	s_cbranch_vccz .LBB0_512
	s_waitcnt vmcnt(0)
	s_cmpk_gt_u32 s6, 0xff
	s_cbranch_scc1 .LBB0_519
	s_barrier

; #define PG8_STAGE(bufoff, gbase, voff) do { _Pragma("unroll") for (int _i = 0; _i < 2; ++_i) \
;         __builtin_amdgcn_global_load_lds((const unsigned*)((const char*)(gbase) + (voff)[_i]), (LAS unsigned*)(lds + (bufoff) + ldsw + _i * 8192), 16, 0, 0); } while (0)
; #define PG8_LDA(dst, b, h) do { _Pragma("unroll") for (int m = 0; m < 4; ++m) _Pragma("unroll") for (int k = 0; k < 2; ++k) dst[m][k] = *(const LAS bf16x8*)(lds + PG8_SA(b, h) + aoff + m * 2048 + k * 1024); } while (0)
; #define PG8_LDB(dst, b, h) do { _Pragma("unroll") for (int n = 0; n < 2; ++n) _Pragma("unroll") for (int k = 0; k < 2; ++k) dst[n][k] = *(const LAS bf16x8*)(lds + PG8_SB(b, h) + boff + n * 2048 + k * 1024); } while (0)
; #define PG8_MMA(ai, bj, At, Bt) do { __builtin_amdgcn_s_setprio(1); _Pragma("unroll") for (int m = 0; m < 4; ++m) _Pragma("unroll") for (int n = 0; n < 2; ++n) _Pragma("unroll") for (int k = 0; k < 2; ++k) \
;         acc[ai][bj][m][n] = __builtin_amdgcn_mfma_f32_16x16x32_bf16(Bt[n][k], At[m][k], acc[ai][bj][m][n], 0, 0, 0); __builtin_amdgcn_s_setprio(0); } while (0)
; #define PG8_BAR __builtin_amdgcn_s_barrier()
; template <class Epi, class Sched>
; __device__ __forceinline__ void gemm_phase(LAS unsigned char* lds, const Gemm g, const Sched& S, const Epi& E) {
;     ...
;         const bool has_next = S.next(ui + 1, nxt);
;         const char* nA = has_next ? (const char*)g.A + (size_t)nxt.pm * tstep : cA; const char* nB = has_next ? (const char*)g.Bt + (size_t)nxt.pn * tstep : cB;
;         for (int t = 0; t < nt; t += 2) {
;             const bool last = (t == nt - 2);
;             const char* a1 = cA + (size_t)(t + 1) * kstep;
;             const char* a2 = last ? nA : cA + (size_t)(t + 2) * kstep; const char* b2 = last ? nB : cB + (size_t)(t + 2) * kstep;
;             const char* a3 = a2 + kstep; const char* b3 = b2 + kstep;
;             if (last && has_next) S.a_ready(nxt);
;             PG8_LDB(B0, 0, 0); PG8_SCHED; PG8_LDA(At, 0, 0); PG8_STAGE(PG8_SA(1, 1), a1 + hstep, voffA);
;             PG8_WAIT_L(8); PG8_BAR; PG8_WAIT_L(0); PG8_MMA(0, 0, At, B0); PG8_BAR; PG8_SCHED;
;             PG8_LDB(B1, 0, 1); PG8_STAGE(PG8_SB(0, 0), b2, voffB);
;             PG8_BAR; PG8_WAIT_L(0); PG8_MMA(0, 1, At, B1); PG8_BAR;
;             PG8_LDA(At, 0, 1); PG8_STAGE(PG8_SA(0, 0), a2, voffA);
;             PG8_BAR; PG8_WAIT_L(0); PG8_MMA(1, 0, At, B0); PG8_BAR; PG8_SCHED;
.LBB0_646:
	s_add_u32 s21, vcc_lo, 0xfffc0080
	s_addc_u32 s22, vcc_hi, -1
	s_add_i32 s23, 16, 0x10000
	v_add_u32_e32 v155, s23, v152
	s_cmp_eq_u32 s20, 12
	s_cselect_b32 s79, s75, s22
	s_cselect_b32 s78, s16, s21
	s_cselect_b32 s71, s17, s19
	s_cselect_b32 s70, s73, s18
	v_lshl_add_u64 v[216:217], vcc, 0, v[148:149]
	s_add_i32 m0, s11, 0xc000
	ds_read_b128 v[172:175], v154
	ds_read_b128 v[188:191], v154 offset:1024
	ds_read_b128 v[192:195], v154 offset:2048
	ds_read_b128 v[196:199], v154 offset:3072
	ds_read_b128 v[200:203], v154 offset:4096
	ds_read_b128 v[204:207], v154 offset:5120
	ds_read_b128 v[208:211], v154 offset:6144
	ds_read_b128 v[212:215], v154 offset:7168
	global_load_lds_dwordx4 v[216:217], off
	v_lshl_add_u64 v[216:217], vcc, 0, v[150:151]
	s_add_i32 m0, s11, 0xe000
	s_nop 0
	global_load_lds_dwordx4 v[216:217], off
	s_waitcnt lgkmcnt(8)
	s_barrier
	s_waitcnt lgkmcnt(0)
	s_setprio 1
	s_waitcnt lgkmcnt(0)
	v_mfma_f32_16x16x32_bf16 v[126:129], v[156:159], v[172:175], v[126:129]
	v_mfma_f32_16x16x32_bf16 v[122:125], v[164:167], v[172:175], v[122:125]
	v_mfma_f32_16x16x32_bf16 v[118:121], v[156:159], v[192:195], v[118:121]
	v_mfma_f32_16x16x32_bf16 v[114:117], v[164:167], v[192:195], v[114:117]
	v_mfma_f32_16x16x32_bf16 v[102:105], v[156:159], v[200:203], v[102:105]
	v_mfma_f32_16x16x32_bf16 v[98:101], v[164:167], v[200:203], v[98:101]
	v_mfma_f32_16x16x32_bf16 v[86:89], v[156:159], v[208:211], v[86:89]
	v_mfma_f32_16x16x32_bf16 v[82:85], v[164:167], v[208:211], v[82:85]
	v_mfma_f32_16x16x32_bf16 v[126:129], v[160:163], v[188:191], v[126:129]
	v_mfma_f32_16x16x32_bf16 v[122:125], v[168:171], v[188:191], v[122:125]
	v_mfma_f32_16x16x32_bf16 v[118:121], v[160:163], v[196:199], v[118:121]
	v_mfma_f32_16x16x32_bf16 v[114:117], v[168:171], v[196:199], v[114:117]
	v_mfma_f32_16x16x32_bf16 v[102:105], v[160:163], v[204:207], v[102:105]
	v_mfma_f32_16x16x32_bf16 v[98:101], v[168:171], v[204:207], v[98:101]
	v_mfma_f32_16x16x32_bf16 v[86:89], v[160:163], v[212:215], v[86:89]
	v_mfma_f32_16x16x32_bf16 v[82:85], v[168:171], v[212:215], v[82:85]
	s_setprio 0
	s_barrier
	s_add_i32 s21, 16, 0x14000
	s_add_i32 s22, s23, s9
	v_add_u32_e32 v155, s21, v152
	v_lshl_add_u64 v[232:233], s[70:71], 0, v[144:145]
	s_mov_b32 m0, s22
	ds_read_b128 v[216:219], v155
	ds_read_b128 v[220:223], v155 offset:1024
	ds_read_b128 v[224:227], v155 offset:2048
	ds_read_b128 v[228:231], v155 offset:3072
	global_load_lds_dwordx4 v[232:233], off
	v_lshl_add_u64 v[234:235], s[70:71], 0, v[140:141]
	s_add_i32 m0, s22, 0x2000
	s_nop 0
	global_load_lds_dwordx4 v[234:235], off
	s_barrier
	s_waitcnt lgkmcnt(0)
	s_setprio 1
	s_waitcnt lgkmcnt(0)
	v_mfma_f32_16x16x32_bf16 v[110:113], v[216:219], v[172:175], v[110:113]
	v_mfma_f32_16x16x32_bf16 v[106:109], v[224:227], v[172:175], v[106:109]
	v_mfma_f32_16x16x32_bf16 v[94:97], v[216:219], v[192:195], v[94:97]
	v_mfma_f32_16x16x32_bf16 v[90:93], v[224:227], v[192:195], v[90:93]
	v_mfma_f32_16x16x32_bf16 v[78:81], v[216:219], v[200:203], v[78:81]
	v_mfma_f32_16x16x32_bf16 v[74:77], v[224:227], v[200:203], v[74:77]
	v_mfma_f32_16x16x32_bf16 v[70:73], v[216:219], v[208:211], v[70:73]
	v_mfma_f32_16x16x32_bf16 v[66:69], v[224:227], v[208:211], v[66:69]
	v_mfma_f32_16x16x32_bf16 v[110:113], v[220:223], v[188:191], v[110:113]
	v_mfma_f32_16x16x32_bf16 v[106:109], v[228:231], v[188:191], v[106:109]
	v_mfma_f32_16x16x32_bf16 v[94:97], v[220:223], v[196:199], v[94:97]
	v_mfma_f32_16x16x32_bf16 v[90:93], v[228:231], v[196:199], v[90:93]
	v_mfma_f32_16x16x32_bf16 v[78:81], v[220:223], v[204:207], v[78:81]
	v_mfma_f32_16x16x32_bf16 v[74:77], v[228:231], v[204:207], v[74:77]
	v_mfma_f32_16x16x32_bf16 v[70:73], v[220:223], v[212:215], v[70:73]
	v_mfma_f32_16x16x32_bf16 v[66:69], v[228:231], v[212:215], v[66:69]
	s_setprio 0
	s_mov_b32 m0, s11
	v_lshl_add_u64 v[236:237], s[78:79], 0, v[146:147]
	s_barrier
	ds_read_b128 v[172:175], v154 offset:16384
	ds_read_b128 v[188:191], v154 offset:17408
	ds_read_b128 v[192:195], v154 offset:18432
	ds_read_b128 v[196:199], v154 offset:19456
	ds_read_b128 v[200:203], v154 offset:20480
	ds_read_b128 v[204:207], v154 offset:21504
	ds_read_b128 v[208:211], v154 offset:22528
	ds_read_b128 v[212:215], v154 offset:23552
	global_load_lds_dwordx4 v[236:237], off
	v_lshl_add_u64 v[238:239], s[78:79], 0, v[142:143]
	s_mov_b32 m0, s41
	s_nop 0
	global_load_lds_dwordx4 v[238:239], off
	s_barrier
	s_waitcnt lgkmcnt(0)
	s_setprio 1
	s_waitcnt lgkmcnt(0)
	v_mfma_f32_16x16x32_bf16 v[62:65], v[156:159], v[172:175], v[62:65]
	v_mfma_f32_16x16x32_bf16 v[58:61], v[164:167], v[172:175], v[58:61]
	v_mfma_f32_16x16x32_bf16 v[54:57], v[156:159], v[192:195], v[54:57]
	v_mfma_f32_16x16x32_bf16 v[50:53], v[164:167], v[192:195], v[50:53]
	v_mfma_f32_16x16x32_bf16 v[38:41], v[156:159], v[200:203], v[38:41]
	v_mfma_f32_16x16x32_bf16 v[34:37], v[164:167], v[200:203], v[34:37]
	v_mfma_f32_16x16x32_bf16 v[22:25], v[156:159], v[208:211], v[22:25]
	v_mfma_f32_16x16x32_bf16 v[18:21], v[164:167], v[208:211], v[18:21]
	v_mfma_f32_16x16x32_bf16 v[62:65], v[160:163], v[188:191], v[62:65]
	v_mfma_f32_16x16x32_bf16 v[58:61], v[168:171], v[188:191], v[58:61]
	v_mfma_f32_16x16x32_bf16 v[54:57], v[160:163], v[196:199], v[54:57]
	v_mfma_f32_16x16x32_bf16 v[50:53], v[168:171], v[196:199], v[50:53]
	v_mfma_f32_16x16x32_bf16 v[38:41], v[160:163], v[204:207], v[38:41]
	v_mfma_f32_16x16x32_bf16 v[34:37], v[168:171], v[204:207], v[34:37]
	v_mfma_f32_16x16x32_bf16 v[22:25], v[160:163], v[212:215], v[22:25]
	v_mfma_f32_16x16x32_bf16 v[18:21], v[168:171], v[212:215], v[18:21]
	s_setprio 0
	s_barrier
; #define PG8_STAGE(bufoff, gbase, voff) do { _Pragma("unroll") for (int _i = 0; _i < 2; ++_i) \
;         __builtin_amdgcn_global_load_lds((const unsigned*)((const char*)(gbase) + (voff)[_i]), (LAS unsigned*)(lds + (bufoff) + ldsw + _i * 8192), 16, 0, 0); } while (0)
; #define PG8_LDA(dst, b, h) do { _Pragma("unroll") for (int m = 0; m < 4; ++m) _Pragma("unroll") for (int k = 0; k < 2; ++k) dst[m][k] = *(const LAS bf16x8*)(lds + PG8_SA(b, h) + aoff + m * 2048 + k * 1024); } while (0)
; #define PG8_LDB(dst, b, h) do { _Pragma("unroll") for (int n = 0; n < 2; ++n) _Pragma("unroll") for (int k = 0; k < 2; ++k) dst[n][k] = *(const LAS bf16x8*)(lds + PG8_SB(b, h) + boff + n * 2048 + k * 1024); } while (0)
; #define PG8_MMA(ai, bj, At, Bt) do { __builtin_amdgcn_s_setprio(1); _Pragma("unroll") for (int m = 0; m < 4; ++m) _Pragma("unroll") for (int n = 0; n < 2; ++n) _Pragma("unroll") for (int k = 0; k < 2; ++k) \
;         acc[ai][bj][m][n] = __builtin_amdgcn_mfma_f32_16x16x32_bf16(Bt[n][k], At[m][k], acc[ai][bj][m][n], 0, 0, 0); __builtin_amdgcn_s_setprio(0); } while (0)
; #define PG8_WAIT_V(n) asm volatile("s_waitcnt vmcnt(" #n ")" ::: "memory")
; #define PG8_WAIT_L(n) asm volatile("s_waitcnt lgkmcnt(" #n ")" ::: "memory")
; #define PG8_BAR __builtin_amdgcn_s_barrier()
; #define PG8_SCHED __builtin_amdgcn_sched_barrier(0)
; template <class Epi, class Sched>
; __device__ __forceinline__ void gemm_phase(LAS unsigned char* lds, const Gemm g, const Sched& S, const Epi& E) {
;     ...
;             PG8_STAGE(PG8_SB(0, 1), b2 + hstep, voffB);
;             PG8_WAIT_V(6); PG8_BAR; PG8_MMA(1, 1, At, B1); PG8_BAR;
;             PG8_LDB(B0, 1, 0); PG8_SCHED; PG8_LDA(At, 1, 0); PG8_STAGE(PG8_SA(0, 1), a2 + hstep, voffA);
;             PG8_WAIT_L(8); PG8_BAR; PG8_WAIT_L(0); PG8_MMA(0, 0, At, B0); PG8_BAR; PG8_SCHED;
;             PG8_LDB(B1, 1, 1); PG8_STAGE(PG8_SB(1, 0), b3, voffB);
;             PG8_BAR; PG8_WAIT_L(0); PG8_MMA(0, 1, At, B1); PG8_BAR;
;             PG8_LDA(At, 1, 1); PG8_STAGE(PG8_SA(1, 0), a3, voffA);
;             PG8_BAR; PG8_WAIT_L(0); PG8_MMA(1, 0, At, B0); PG8_BAR; PG8_SCHED;
	s_add_u32 s22, s70, 0x40000
	s_addc_u32 s23, s71, 0
	s_add_i32 s21, s21, s9
	v_lshl_add_u64 v[156:157], s[22:23], 0, v[144:145]
	s_mov_b32 m0, s21
	s_nop 0
	global_load_lds_dwordx4 v[156:157], off
	v_lshl_add_u64 v[156:157], s[22:23], 0, v[140:141]
	s_add_i32 m0, s21, 0x2000
	s_nop 0
	global_load_lds_dwordx4 v[156:157], off
	s_waitcnt vmcnt(6)
	s_barrier
	s_setprio 1
	v_mfma_f32_16x16x32_bf16 v[46:49], v[216:219], v[172:175], v[46:49]
	v_add_u32_e32 v155, 0x18010, v152
	v_mfma_f32_16x16x32_bf16 v[42:45], v[224:227], v[172:175], v[42:45]
	ds_read_b128 v[156:159], v155
	v_mfma_f32_16x16x32_bf16 v[30:33], v[216:219], v[192:195], v[30:33]
	ds_read_b128 v[160:163], v155 offset:1024
	v_mfma_f32_16x16x32_bf16 v[26:29], v[224:227], v[192:195], v[26:29]
	ds_read_b128 v[164:167], v155 offset:2048
	v_mfma_f32_16x16x32_bf16 v[14:17], v[216:219], v[200:203], v[14:17]
	ds_read_b128 v[168:171], v155 offset:3072
	v_mfma_f32_16x16x32_bf16 v[10:13], v[224:227], v[200:203], v[10:13]
	v_mfma_f32_16x16x32_bf16 v[4:7], v[216:219], v[208:211], v[4:7]
	v_mfma_f32_16x16x32_bf16 v[0:3], v[224:227], v[208:211], v[0:3]
	v_mfma_f32_16x16x32_bf16 v[46:49], v[220:223], v[188:191], v[46:49]
	v_mfma_f32_16x16x32_bf16 v[42:45], v[228:231], v[188:191], v[42:45]
	v_mfma_f32_16x16x32_bf16 v[30:33], v[220:223], v[196:199], v[30:33]
	v_mfma_f32_16x16x32_bf16 v[26:29], v[228:231], v[196:199], v[26:29]
	v_mfma_f32_16x16x32_bf16 v[14:17], v[220:223], v[204:207], v[14:17]
	v_mfma_f32_16x16x32_bf16 v[10:13], v[228:231], v[204:207], v[10:13]
	v_mfma_f32_16x16x32_bf16 v[4:7], v[220:223], v[212:215], v[4:7]
	v_mfma_f32_16x16x32_bf16 v[0:3], v[228:231], v[212:215], v[0:3]
	s_setprio 0
	s_add_i32 s21, 16, 0x18000
	v_add_u32_e32 v155, s21, v152
	s_barrier
	s_add_u32 s22, s78, 0x40000
	s_addc_u32 s23, s79, 0
	s_mov_b32 m0, s12
	v_lshl_add_u64 v[216:217], s[22:23], 0, v[146:147]
	ds_read_b128 v[172:175], v154 offset:32768
	ds_read_b128 v[188:191], v154 offset:33792
	ds_read_b128 v[192:195], v154 offset:34816
	ds_read_b128 v[196:199], v154 offset:35840
	ds_read_b128 v[200:203], v154 offset:36864
	ds_read_b128 v[204:207], v154 offset:37888
	ds_read_b128 v[208:211], v154 offset:38912
	ds_read_b128 v[212:215], v154 offset:39936
	global_load_lds_dwordx4 v[216:217], off
	v_lshl_add_u64 v[216:217], s[22:23], 0, v[142:143]
	s_mov_b32 m0, s13
	s_nop 0
	global_load_lds_dwordx4 v[216:217], off
	s_waitcnt lgkmcnt(8)
	s_barrier
	s_waitcnt lgkmcnt(0)
	s_setprio 1
	s_waitcnt lgkmcnt(0)
	v_mfma_f32_16x16x32_bf16 v[126:129], v[156:159], v[172:175], v[126:129]
	v_mfma_f32_16x16x32_bf16 v[122:125], v[164:167], v[172:175], v[122:125]
	v_mfma_f32_16x16x32_bf16 v[118:121], v[156:159], v[192:195], v[118:121]
	v_mfma_f32_16x16x32_bf16 v[114:117], v[164:167], v[192:195], v[114:117]
	v_mfma_f32_16x16x32_bf16 v[102:105], v[156:159], v[200:203], v[102:105]
	v_mfma_f32_16x16x32_bf16 v[98:101], v[164:167], v[200:203], v[98:101]
	v_mfma_f32_16x16x32_bf16 v[86:89], v[156:159], v[208:211], v[86:89]
	v_mfma_f32_16x16x32_bf16 v[82:85], v[164:167], v[208:211], v[82:85]
	v_mfma_f32_16x16x32_bf16 v[126:129], v[160:163], v[188:191], v[126:129]
	v_mfma_f32_16x16x32_bf16 v[122:125], v[168:171], v[188:191], v[122:125]
	v_mfma_f32_16x16x32_bf16 v[118:121], v[160:163], v[196:199], v[118:121]
	v_mfma_f32_16x16x32_bf16 v[114:117], v[168:171], v[196:199], v[114:117]
	v_mfma_f32_16x16x32_bf16 v[102:105], v[160:163], v[204:207], v[102:105]
	v_mfma_f32_16x16x32_bf16 v[98:101], v[168:171], v[204:207], v[98:101]
	v_mfma_f32_16x16x32_bf16 v[86:89], v[160:163], v[212:215], v[86:89]
	v_mfma_f32_16x16x32_bf16 v[82:85], v[168:171], v[212:215], v[82:85]
	s_setprio 0
	s_barrier
	s_add_i32 s78, 16, 0x1c000
	s_add_i32 s21, s21, s9
	v_add_u32_e32 v155, s78, v152
	v_lshl_add_u64 v[232:233], v[232:233], 0, s[94:95]
	s_mov_b32 m0, s21
	ds_read_b128 v[216:219], v155
	ds_read_b128 v[220:223], v155 offset:1024
	ds_read_b128 v[224:227], v155 offset:2048
	ds_read_b128 v[228:231], v155 offset:3072
	global_load_lds_dwordx4 v[232:233], off
	v_lshl_add_u64 v[232:233], v[234:235], 0, s[94:95]
	s_add_i32 m0, s21, 0x2000
	s_nop 0
	global_load_lds_dwordx4 v[232:233], off
	s_barrier
	s_waitcnt lgkmcnt(0)
	s_setprio 1
	s_waitcnt lgkmcnt(0)
	v_mfma_f32_16x16x32_bf16 v[110:113], v[216:219], v[172:175], v[110:113]
	v_mfma_f32_16x16x32_bf16 v[106:109], v[224:227], v[172:175], v[106:109]
	v_mfma_f32_16x16x32_bf16 v[94:97], v[216:219], v[192:195], v[94:97]
	v_mfma_f32_16x16x32_bf16 v[90:93], v[224:227], v[192:195], v[90:93]
	v_mfma_f32_16x16x32_bf16 v[78:81], v[216:219], v[200:203], v[78:81]
	v_mfma_f32_16x16x32_bf16 v[74:77], v[224:227], v[200:203], v[74:77]
	v_mfma_f32_16x16x32_bf16 v[70:73], v[216:219], v[208:211], v[70:73]
	v_mfma_f32_16x16x32_bf16 v[66:69], v[224:227], v[208:211], v[66:69]
	v_mfma_f32_16x16x32_bf16 v[110:113], v[220:223], v[188:191], v[110:113]
	v_mfma_f32_16x16x32_bf16 v[106:109], v[228:231], v[188:191], v[106:109]
	v_mfma_f32_16x16x32_bf16 v[94:97], v[220:223], v[196:199], v[94:97]
	v_mfma_f32_16x16x32_bf16 v[90:93], v[228:231], v[196:199], v[90:93]
	v_mfma_f32_16x16x32_bf16 v[78:81], v[220:223], v[204:207], v[78:81]
	v_mfma_f32_16x16x32_bf16 v[74:77], v[228:231], v[204:207], v[74:77]
	v_mfma_f32_16x16x32_bf16 v[70:73], v[220:223], v[212:215], v[70:73]
	v_mfma_f32_16x16x32_bf16 v[66:69], v[228:231], v[212:215], v[66:69]
	s_setprio 0
	s_mov_b32 m0, s14
	v_lshl_add_u64 v[232:233], v[236:237], 0, s[94:95]
	s_barrier
; #define PG8_STAGE(bufoff, gbase, voff) do { _Pragma("unroll") for (int _i = 0; _i < 2; ++_i) \
;         __builtin_amdgcn_global_load_lds((const unsigned*)((const char*)(gbase) + (voff)[_i]), (LAS unsigned*)(lds + (bufoff) + ldsw + _i * 8192), 16, 0, 0); } while (0)
; #define PG8_LDA(dst, b, h) do { _Pragma("unroll") for (int m = 0; m < 4; ++m) _Pragma("unroll") for (int k = 0; k < 2; ++k) dst[m][k] = *(const LAS bf16x8*)(lds + PG8_SA(b, h) + aoff + m * 2048 + k * 1024); } while (0)
; #define PG8_LDB(dst, b, h) do { _Pragma("unroll") for (int n = 0; n < 2; ++n) _Pragma("unroll") for (int k = 0; k < 2; ++k) dst[n][k] = *(const LAS bf16x8*)(lds + PG8_SB(b, h) + boff + n * 2048 + k * 1024); } while (0)
; #define PG8_MMA(ai, bj, At, Bt) do { __builtin_amdgcn_s_setprio(1); _Pragma("unroll") for (int m = 0; m < 4; ++m) _Pragma("unroll") for (int n = 0; n < 2; ++n) _Pragma("unroll") for (int k = 0; k < 2; ++k) \
;         acc[ai][bj][m][n] = __builtin_amdgcn_mfma_f32_16x16x32_bf16(Bt[n][k], At[m][k], acc[ai][bj][m][n], 0, 0, 0); __builtin_amdgcn_s_setprio(0); } while (0)
; #define PG8_WAIT_V(n) asm volatile("s_waitcnt vmcnt(" #n ")" ::: "memory")
; #define PG8_WAIT_L(n) asm volatile("s_waitcnt lgkmcnt(" #n ")" ::: "memory")
; #define PG8_BAR __builtin_amdgcn_s_barrier()
; #define PG8_SCHED __builtin_amdgcn_sched_barrier(0)
; template <class Epi, class Sched>
; __device__ __forceinline__ void gemm_phase(LAS unsigned char* lds, const Gemm g, const Sched& S, const Epi& E) {
;     ...
;             PG8_LDB(B0, 0, 0); PG8_SCHED; PG8_LDA(At, 0, 0); PG8_STAGE(PG8_SA(1, 1), a1 + hstep, voffA);
;     ...
;             PG8_LDA(At, 1, 1); PG8_STAGE(PG8_SA(1, 0), a3, voffA);
;             PG8_BAR; PG8_WAIT_L(0); PG8_MMA(1, 0, At, B0); PG8_BAR; PG8_SCHED;
;             PG8_STAGE(PG8_SB(1, 1), b3 + hstep, voffB);
;             PG8_WAIT_V(6); PG8_BAR; PG8_MMA(1, 1, At, B1); PG8_BAR;
;         }
	ds_read_b128 v[172:175], v154 offset:49152
	ds_read_b128 v[188:191], v154 offset:50176
	ds_read_b128 v[192:195], v154 offset:51200
	ds_read_b128 v[196:199], v154 offset:52224
	ds_read_b128 v[200:203], v154 offset:53248
	ds_read_b128 v[204:207], v154 offset:54272
	ds_read_b128 v[208:211], v154 offset:55296
	ds_read_b128 v[212:215], v154 offset:56320
	global_load_lds_dwordx4 v[232:233], off
	v_lshl_add_u64 v[232:233], v[238:239], 0, s[94:95]
	s_mov_b32 m0, s15
	s_nop 0
	global_load_lds_dwordx4 v[232:233], off
	s_barrier
	s_waitcnt lgkmcnt(0)
	s_setprio 1
	s_waitcnt lgkmcnt(0)
	v_mfma_f32_16x16x32_bf16 v[62:65], v[156:159], v[172:175], v[62:65]
	v_mfma_f32_16x16x32_bf16 v[58:61], v[164:167], v[172:175], v[58:61]
	v_mfma_f32_16x16x32_bf16 v[54:57], v[156:159], v[192:195], v[54:57]
	v_mfma_f32_16x16x32_bf16 v[50:53], v[164:167], v[192:195], v[50:53]
	v_mfma_f32_16x16x32_bf16 v[38:41], v[156:159], v[200:203], v[38:41]
	v_mfma_f32_16x16x32_bf16 v[34:37], v[164:167], v[200:203], v[34:37]
	v_mfma_f32_16x16x32_bf16 v[22:25], v[156:159], v[208:211], v[22:25]
	v_mfma_f32_16x16x32_bf16 v[18:21], v[164:167], v[208:211], v[18:21]
	v_mfma_f32_16x16x32_bf16 v[62:65], v[160:163], v[188:191], v[62:65]
	v_mfma_f32_16x16x32_bf16 v[58:61], v[168:171], v[188:191], v[58:61]
	v_mfma_f32_16x16x32_bf16 v[54:57], v[160:163], v[196:199], v[54:57]
	v_mfma_f32_16x16x32_bf16 v[50:53], v[168:171], v[196:199], v[50:53]
	v_mfma_f32_16x16x32_bf16 v[38:41], v[160:163], v[204:207], v[38:41]
	v_mfma_f32_16x16x32_bf16 v[34:37], v[168:171], v[204:207], v[34:37]
	v_mfma_f32_16x16x32_bf16 v[22:25], v[160:163], v[212:215], v[22:25]
	v_mfma_f32_16x16x32_bf16 v[18:21], v[168:171], v[212:215], v[18:21]
	s_setprio 0
	s_barrier
	s_add_u32 s22, s70, 0x40080
	s_addc_u32 s23, s71, 0
	s_add_i32 s21, s78, s9
	v_lshl_add_u64 v[156:157], s[22:23], 0, v[144:145]
	s_mov_b32 m0, s21
	s_nop 0
	global_load_lds_dwordx4 v[156:157], off
	v_lshl_add_u64 v[156:157], s[22:23], 0, v[140:141]
	s_add_i32 m0, s21, 0x2000
	s_nop 0
	global_load_lds_dwordx4 v[156:157], off
	s_waitcnt vmcnt(6)
	s_barrier
	s_setprio 1
	v_mfma_f32_16x16x32_bf16 v[46:49], v[216:219], v[172:175], v[46:49]
	v_add_u32_e32 v155, 0x10010, v152
	v_mfma_f32_16x16x32_bf16 v[42:45], v[224:227], v[172:175], v[42:45]
	ds_read_b128 v[156:159], v155
	v_mfma_f32_16x16x32_bf16 v[30:33], v[216:219], v[192:195], v[30:33]
	ds_read_b128 v[160:163], v155 offset:1024
	v_mfma_f32_16x16x32_bf16 v[26:29], v[224:227], v[192:195], v[26:29]
	ds_read_b128 v[164:167], v155 offset:2048
	v_mfma_f32_16x16x32_bf16 v[14:17], v[216:219], v[200:203], v[14:17]
	ds_read_b128 v[168:171], v155 offset:3072
	v_mfma_f32_16x16x32_bf16 v[10:13], v[224:227], v[200:203], v[10:13]
	v_mfma_f32_16x16x32_bf16 v[4:7], v[216:219], v[208:211], v[4:7]
	v_mfma_f32_16x16x32_bf16 v[0:3], v[224:227], v[208:211], v[0:3]
	v_mfma_f32_16x16x32_bf16 v[46:49], v[220:223], v[188:191], v[46:49]
	v_mfma_f32_16x16x32_bf16 v[42:45], v[228:231], v[188:191], v[42:45]
	v_mfma_f32_16x16x32_bf16 v[30:33], v[220:223], v[196:199], v[30:33]
	v_mfma_f32_16x16x32_bf16 v[26:29], v[228:231], v[196:199], v[26:29]
	v_mfma_f32_16x16x32_bf16 v[14:17], v[220:223], v[204:207], v[14:17]
	v_mfma_f32_16x16x32_bf16 v[10:13], v[228:231], v[204:207], v[10:13]
	v_mfma_f32_16x16x32_bf16 v[4:7], v[220:223], v[212:215], v[4:7]
	v_mfma_f32_16x16x32_bf16 v[0:3], v[228:231], v[212:215], v[0:3]
	s_setprio 0
	s_add_i32 s20, s20, 2
	s_add_u32 vcc_lo, vcc_lo, 0x100
	s_addc_u32 vcc_hi, vcc_hi, 0
	s_add_u32 s18, s18, 0x100
	s_addc_u32 s19, s19, 0
	s_cmp_gt_u32 s20, 13
	s_barrier
	s_cbranch_scc0 .LBB0_646
; __device__ __forceinline__ unsigned pk_bf16(float a, float b) { f32x2 v = {a, b}; bf2_t r = __builtin_convertvector(v, bf2_t); return __builtin_bit_cast(unsigned, r); }
; #define PG8_WAIT_V(n) asm volatile("s_waitcnt vmcnt(" #n ")" ::: "memory")
; #define PG8_BAR __builtin_amdgcn_s_barrier()
;     __device__ __forceinline__ void operator()(const f32x4 (&acc)[2][2][4][2], const Unit& u, int wr, int wc, int fr, int fq) const {
;         const int row0 = u.pm * BM + wr * 64 + fr; int colt = u.pn * BM; bf16_t* base = O;
;         if (split_cols) { const int t = colt / split_cols; base += (size_t)t * split_stride; colt -= t * split_cols; }
;         const int col0 = colt + wc * 32 + 8 * fq;
; #pragma unroll
;         for (int ai = 0; ai < 2; ++ai)
; #pragma unroll
;             for (int m = 0; m < 4; ++m) { const int row = row0 + ai * HALF + m * 16;
;                 bf16_t* rowp = slot_stride ? base + (size_t)(colt >> 7) * slot_stride + (size_t)row * 128 + wc * 32 + 8 * fq : base + (size_t)row * ldc + col0;
; #pragma unroll
;                 for (int bj = 0; bj < 2; ++bj) { const f32x4 v0 = acc[ai][bj][m][0], v1 = acc[ai][bj][m][1];
;                     u32x4 w; w.x = pk_bf16(v0[0], v0[1]); w.y = pk_bf16(v0[2], v0[3]); w.z = pk_bf16(v1[0], v1[1]); w.w = pk_bf16(v1[2], v1[3]);
;                     *(u32x4*)(rowp + (slot_stride ? (size_t)bj * slot_stride : (size_t)bj * HALF)) = w; } }
; template <class Epi, class Sched>
; __device__ __forceinline__ void gemm_phase(LAS unsigned char* lds, const Gemm g, const Sched& S, const Epi& E) {
;     ...
;         E(acc, cur, wr, wc, fr, fq); S.done(cur);
;         if (!has_next) break;
; #pragma unroll
;         for (int a = 0; a < 2; ++a)
; #pragma unroll
;             for (int b = 0; b < 2; ++b)
; #pragma unroll
;                 for (int m = 0; m < 4; ++m)
; #pragma unroll
;                     for (int n = 0; n < 2; ++n) acc[a][b][m][n] = (f32x4){0.f, 0.f, 0.f, 0.f};
;         cur = nxt; cA = nA; cB = nB; ++ui;
;     }
;     PG8_WAIT_V(0);
;     if (wr == 0) PG8_BAR;
;     PG8_BAR;
	s_waitcnt lgkmcnt(0)
	s_mul_hi_i32 s16, s40, 0x2e8ba2e9
	s_lshr_b32 s17, s16, 31
	s_ashr_i32 s16, s16, 1
	s_add_i32 s19, s16, s17
	s_lshl_b32 s18, s40, 8
	s_mul_i32 s16, s19, 0xbb00000
	s_mul_hi_i32 s17, s19, 0xbb00000
	s_add_u32 s16, s82, s16
	s_mulk_i32 s19, 0xf500
	s_addc_u32 s17, s83, s17
	s_add_i32 s19, s19, s18
	v_or_b32_e32 v156, s19, v153
	v_lshl_add_u32 v155, s42, 8, v9
	v_ashrrev_i32_e32 v157, 31, v156
	v_lshl_add_u64 v[156:157], v[156:157], 1, s[16:17]
	v_cvt_pk_bf16_f32 v70, v70, v71
	v_cvt_pk_bf16_f32 v71, v72, v73
	v_cvt_pk_bf16_f32 v72, v66, v67
	v_add_u32_e32 v66, 0x80, v155
	v_mad_i64_i32 v[158:159], s[16:17], v155, s81, v[156:157]
	v_cvt_pk_bf16_f32 v110, v110, v111
	v_cvt_pk_bf16_f32 v111, v112, v113
	v_cvt_pk_bf16_f32 v112, v106, v107
	v_cvt_pk_bf16_f32 v113, v108, v109
	v_or_b32_e32 v106, 16, v155
	v_mad_i64_i32 v[66:67], s[16:17], v66, s81, v[156:157]
	v_cvt_pk_bf16_f32 v46, v46, v47
	v_cvt_pk_bf16_f32 v47, v48, v49
	v_cvt_pk_bf16_f32 v48, v42, v43
	v_cvt_pk_bf16_f32 v49, v44, v45
	v_add_u32_e32 v42, 0x90, v155
	global_store_dwordx4 v[158:159], v[110:113], off offset:256
	v_cvt_pk_bf16_f32 v94, v94, v95
	v_cvt_pk_bf16_f32 v95, v96, v97
	v_mad_i64_i32 v[110:111], s[16:17], v106, s81, v[156:157]
	v_cvt_pk_bf16_f32 v96, v90, v91
	v_cvt_pk_bf16_f32 v97, v92, v93
	v_or_b32_e32 v90, 32, v155
	global_store_dwordx4 v[66:67], v[46:49], off offset:256
	v_cvt_pk_bf16_f32 v30, v30, v31
	v_cvt_pk_bf16_f32 v31, v32, v33
	v_mad_i64_i32 v[46:47], s[16:17], v42, s81, v[156:157]
	v_cvt_pk_bf16_f32 v32, v26, v27
	v_cvt_pk_bf16_f32 v33, v28, v29
	v_add_u32_e32 v26, 0xa0, v155
	global_store_dwordx4 v[110:111], v[94:97], off offset:256
	v_cvt_pk_bf16_f32 v78, v78, v79
	v_cvt_pk_bf16_f32 v79, v80, v81
	v_mad_i64_i32 v[94:95], s[16:17], v90, s81, v[156:157]
	v_cvt_pk_bf16_f32 v80, v74, v75
	v_cvt_pk_bf16_f32 v81, v76, v77
	v_or_b32_e32 v74, 48, v155
	global_store_dwordx4 v[46:47], v[30:33], off offset:256
	v_cvt_pk_bf16_f32 v14, v14, v15
	v_cvt_pk_bf16_f32 v15, v16, v17
	v_mad_i64_i32 v[30:31], s[16:17], v26, s81, v[156:157]
	v_cvt_pk_bf16_f32 v16, v10, v11
	v_cvt_pk_bf16_f32 v17, v12, v13
	v_add_u32_e32 v10, 0xb0, v155
	v_cvt_pk_bf16_f32 v126, v126, v127
	v_cvt_pk_bf16_f32 v127, v128, v129
	v_cvt_pk_bf16_f32 v128, v122, v123
	v_cvt_pk_bf16_f32 v129, v124, v125
	v_cvt_pk_bf16_f32 v106, v118, v119
	v_cvt_pk_bf16_f32 v107, v120, v121
	v_cvt_pk_bf16_f32 v108, v114, v115
	v_cvt_pk_bf16_f32 v109, v116, v117
	v_cvt_pk_bf16_f32 v90, v102, v103
	v_cvt_pk_bf16_f32 v91, v104, v105
	v_cvt_pk_bf16_f32 v92, v98, v99
	v_cvt_pk_bf16_f32 v93, v100, v101
	global_store_dwordx4 v[94:95], v[78:81], off offset:256
	v_cvt_pk_bf16_f32 v75, v88, v89
	v_cvt_pk_bf16_f32 v76, v82, v83
	v_mad_i64_i32 v[78:79], s[16:17], v74, s81, v[156:157]
	v_cvt_pk_bf16_f32 v74, v86, v87
	v_cvt_pk_bf16_f32 v77, v84, v85
	v_cvt_pk_bf16_f32 v73, v68, v69
	v_cvt_pk_bf16_f32 v62, v62, v63
	v_cvt_pk_bf16_f32 v63, v64, v65
	v_cvt_pk_bf16_f32 v64, v58, v59
	v_cvt_pk_bf16_f32 v65, v60, v61
	v_cvt_pk_bf16_f32 v42, v54, v55
	v_cvt_pk_bf16_f32 v43, v56, v57
	v_cvt_pk_bf16_f32 v44, v50, v51
	v_cvt_pk_bf16_f32 v45, v52, v53
	v_cvt_pk_bf16_f32 v26, v38, v39
	v_cvt_pk_bf16_f32 v27, v40, v41
	v_cvt_pk_bf16_f32 v28, v34, v35
	v_cvt_pk_bf16_f32 v29, v36, v37
	global_store_dwordx4 v[30:31], v[14:17], off offset:256
	v_cvt_pk_bf16_f32 v11, v24, v25
	v_cvt_pk_bf16_f32 v12, v18, v19
	v_mad_i64_i32 v[14:15], s[16:17], v10, s81, v[156:157]
	v_cvt_pk_bf16_f32 v10, v22, v23
	v_cvt_pk_bf16_f32 v13, v20, v21
	v_cvt_pk_bf16_f32 v4, v4, v5
	v_cvt_pk_bf16_f32 v5, v6, v7
	v_cvt_pk_bf16_f32 v6, v0, v1
	v_cvt_pk_bf16_f32 v7, v2, v3
	s_and_b64 vcc, exec, s[38:39]
	s_mov_b32 s40, s72
	s_mov_b32 s42, s74
	s_mov_b64 s[70:71], s[88:89]
	s_mov_b64 s[78:79], s[66:67]
	global_store_dwordx4 v[158:159], v[126:129], off
	global_store_dwordx4 v[110:111], v[106:109], off
	global_store_dwordx4 v[94:95], v[90:93], off
	global_store_dwordx4 v[78:79], v[74:77], off
	global_store_dwordx4 v[78:79], v[70:73], off offset:256
	global_store_dwordx4 v[66:67], v[62:65], off
	global_store_dwordx4 v[46:47], v[42:45], off
	global_store_dwordx4 v[30:31], v[26:29], off
	global_store_dwordx4 v[14:15], v[10:13], off
	global_store_dwordx4 v[14:15], v[4:7], off offset:256
	s_cbranch_vccz .LBB0_643
	s_waitcnt vmcnt(0)
	s_cmpk_gt_u32 s6, 0xff
	s_cbranch_scc1 .LBB0_650
	s_barrier

; #define PG8_STAGE(bufoff, gbase, voff) do { _Pragma("unroll") for (int _i = 0; _i < 2; ++_i) \
;         __builtin_amdgcn_global_load_lds((const unsigned*)((const char*)(gbase) + (voff)[_i]), (LAS unsigned*)(lds + (bufoff) + ldsw + _i * 8192), 16, 0, 0); } while (0)
; #define PG8_LDA(dst, b, h) do { _Pragma("unroll") for (int m = 0; m < 4; ++m) _Pragma("unroll") for (int k = 0; k < 2; ++k) dst[m][k] = *(const LAS bf16x8*)(lds + PG8_SA(b, h) + aoff + m * 2048 + k * 1024); } while (0)
; #define PG8_LDB(dst, b, h) do { _Pragma("unroll") for (int n = 0; n < 2; ++n) _Pragma("unroll") for (int k = 0; k < 2; ++k) dst[n][k] = *(const LAS bf16x8*)(lds + PG8_SB(b, h) + boff + n * 2048 + k * 1024); } while (0)
; #define PG8_MMA(ai, bj, At, Bt) do { __builtin_amdgcn_s_setprio(1); _Pragma("unroll") for (int m = 0; m < 4; ++m) _Pragma("unroll") for (int n = 0; n < 2; ++n) _Pragma("unroll") for (int k = 0; k < 2; ++k) \
;         acc[ai][bj][m][n] = __builtin_amdgcn_mfma_f32_16x16x32_bf16(Bt[n][k], At[m][k], acc[ai][bj][m][n], 0, 0, 0); __builtin_amdgcn_s_setprio(0); } while (0)
; #define PG8_BAR __builtin_amdgcn_s_barrier()
; template <class Epi, class Sched>
; __device__ __forceinline__ void gemm_phase(LAS unsigned char* lds, const Gemm g, const Sched& S, const Epi& E) {
;     ...
;         const bool has_next = S.next(ui + 1, nxt);
;         const char* nA = has_next ? (const char*)g.A + (size_t)nxt.pm * tstep : cA; const char* nB = has_next ? (const char*)g.Bt + (size_t)nxt.pn * tstep : cB;
;         for (int t = 0; t < nt; t += 2) {
;             const bool last = (t == nt - 2);
;             const char* a1 = cA + (size_t)(t + 1) * kstep;
;             const char* a2 = last ? nA : cA + (size_t)(t + 2) * kstep; const char* b2 = last ? nB : cB + (size_t)(t + 2) * kstep;
;             const char* a3 = a2 + kstep; const char* b3 = b2 + kstep;
;             if (last && has_next) S.a_ready(nxt);
;             PG8_LDB(B0, 0, 0); PG8_SCHED; PG8_LDA(At, 0, 0); PG8_STAGE(PG8_SA(1, 1), a1 + hstep, voffA);
;             PG8_WAIT_L(8); PG8_BAR; PG8_WAIT_L(0); PG8_MMA(0, 0, At, B0); PG8_BAR; PG8_SCHED;
;             PG8_LDB(B1, 0, 1); PG8_STAGE(PG8_SB(0, 0), b2, voffB);
;             PG8_BAR; PG8_WAIT_L(0); PG8_MMA(0, 1, At, B1); PG8_BAR;
;             PG8_LDA(At, 0, 1); PG8_STAGE(PG8_SA(0, 0), a2, voffA);
;             PG8_BAR; PG8_WAIT_L(0); PG8_MMA(1, 0, At, B0); PG8_BAR; PG8_SCHED;
.LBB0_825:
	s_add_u32 s72, s42, 0x100
	s_addc_u32 s73, s43, 0
	s_add_i32 s19, 16, 0x10000
	v_add_u32_e32 v155, s19, v152
	s_cmp_eq_u32 s18, 40
	s_cselect_b32 s71, s41, s73
	s_cselect_b32 s70, s40, s72
	s_cselect_b32 s67, s1, s17
	s_cselect_b32 s66, s0, s16
	v_lshl_add_u64 v[216:217], s[42:43], 0, v[148:149]
	s_add_i32 m0, s11, 0xc000
	ds_read_b128 v[172:175], v154
	ds_read_b128 v[188:191], v154 offset:1024
	ds_read_b128 v[192:195], v154 offset:2048
	ds_read_b128 v[196:199], v154 offset:3072
	ds_read_b128 v[200:203], v154 offset:4096
	ds_read_b128 v[204:207], v154 offset:5120
	ds_read_b128 v[208:211], v154 offset:6144
	ds_read_b128 v[212:215], v154 offset:7168
	global_load_lds_dwordx4 v[216:217], off
	v_lshl_add_u64 v[216:217], s[42:43], 0, v[150:151]
	s_add_i32 m0, s11, 0xe000
	s_nop 0
	global_load_lds_dwordx4 v[216:217], off
	s_waitcnt lgkmcnt(8)
	s_barrier
	s_waitcnt lgkmcnt(0)
	s_setprio 1
	s_waitcnt lgkmcnt(0)
	v_mfma_f32_16x16x32_bf16 v[126:129], v[156:159], v[172:175], v[126:129]
	v_mfma_f32_16x16x32_bf16 v[122:125], v[164:167], v[172:175], v[122:125]
	v_mfma_f32_16x16x32_bf16 v[118:121], v[156:159], v[192:195], v[118:121]
	v_mfma_f32_16x16x32_bf16 v[114:117], v[164:167], v[192:195], v[114:117]
	v_mfma_f32_16x16x32_bf16 v[102:105], v[156:159], v[200:203], v[102:105]
	v_mfma_f32_16x16x32_bf16 v[98:101], v[164:167], v[200:203], v[98:101]
	v_mfma_f32_16x16x32_bf16 v[86:89], v[156:159], v[208:211], v[86:89]
	v_mfma_f32_16x16x32_bf16 v[82:85], v[164:167], v[208:211], v[82:85]
	v_mfma_f32_16x16x32_bf16 v[126:129], v[160:163], v[188:191], v[126:129]
	v_mfma_f32_16x16x32_bf16 v[122:125], v[168:171], v[188:191], v[122:125]
	v_mfma_f32_16x16x32_bf16 v[118:121], v[160:163], v[196:199], v[118:121]
	v_mfma_f32_16x16x32_bf16 v[114:117], v[168:171], v[196:199], v[114:117]
	v_mfma_f32_16x16x32_bf16 v[102:105], v[160:163], v[204:207], v[102:105]
	v_mfma_f32_16x16x32_bf16 v[98:101], v[168:171], v[204:207], v[98:101]
	v_mfma_f32_16x16x32_bf16 v[86:89], v[160:163], v[212:215], v[86:89]
	v_mfma_f32_16x16x32_bf16 v[82:85], v[168:171], v[212:215], v[82:85]
	s_setprio 0
	s_barrier
	s_add_i32 s22, 16, 0x14000
	s_add_i32 s19, s19, s9
	v_add_u32_e32 v155, s22, v152
	v_lshl_add_u64 v[232:233], s[66:67], 0, v[144:145]
	s_mov_b32 m0, s19
	ds_read_b128 v[216:219], v155
	ds_read_b128 v[220:223], v155 offset:1024
	ds_read_b128 v[224:227], v155 offset:2048
	ds_read_b128 v[228:231], v155 offset:3072
	global_load_lds_dwordx4 v[232:233], off
	v_lshl_add_u64 v[234:235], s[66:67], 0, v[140:141]
	s_add_i32 m0, s19, 0x2000
	s_nop 0
	global_load_lds_dwordx4 v[234:235], off
	s_barrier
	s_waitcnt lgkmcnt(0)
	s_setprio 1
	s_waitcnt lgkmcnt(0)
	v_mfma_f32_16x16x32_bf16 v[110:113], v[216:219], v[172:175], v[110:113]
	v_mfma_f32_16x16x32_bf16 v[106:109], v[224:227], v[172:175], v[106:109]
	v_mfma_f32_16x16x32_bf16 v[94:97], v[216:219], v[192:195], v[94:97]
	v_mfma_f32_16x16x32_bf16 v[90:93], v[224:227], v[192:195], v[90:93]
	v_mfma_f32_16x16x32_bf16 v[78:81], v[216:219], v[200:203], v[78:81]
	v_mfma_f32_16x16x32_bf16 v[74:77], v[224:227], v[200:203], v[74:77]
	v_mfma_f32_16x16x32_bf16 v[70:73], v[216:219], v[208:211], v[70:73]
	v_mfma_f32_16x16x32_bf16 v[66:69], v[224:227], v[208:211], v[66:69]
	v_mfma_f32_16x16x32_bf16 v[110:113], v[220:223], v[188:191], v[110:113]
	v_mfma_f32_16x16x32_bf16 v[106:109], v[228:231], v[188:191], v[106:109]
	v_mfma_f32_16x16x32_bf16 v[94:97], v[220:223], v[196:199], v[94:97]
	v_mfma_f32_16x16x32_bf16 v[90:93], v[228:231], v[196:199], v[90:93]
	v_mfma_f32_16x16x32_bf16 v[78:81], v[220:223], v[204:207], v[78:81]
	v_mfma_f32_16x16x32_bf16 v[74:77], v[228:231], v[204:207], v[74:77]
	v_mfma_f32_16x16x32_bf16 v[70:73], v[220:223], v[212:215], v[70:73]
	v_mfma_f32_16x16x32_bf16 v[66:69], v[228:231], v[212:215], v[66:69]
	s_setprio 0
	s_mov_b32 m0, s11
	v_lshl_add_u64 v[236:237], s[70:71], 0, v[146:147]
	s_barrier
	ds_read_b128 v[172:175], v154 offset:16384
	ds_read_b128 v[188:191], v154 offset:17408
	ds_read_b128 v[192:195], v154 offset:18432
	ds_read_b128 v[196:199], v154 offset:19456
	ds_read_b128 v[200:203], v154 offset:20480
	ds_read_b128 v[204:207], v154 offset:21504
	ds_read_b128 v[208:211], v154 offset:22528
	ds_read_b128 v[212:215], v154 offset:23552
	global_load_lds_dwordx4 v[236:237], off
	v_lshl_add_u64 v[238:239], s[70:71], 0, v[142:143]
	s_mov_b32 m0, s74
	s_nop 0
	global_load_lds_dwordx4 v[238:239], off
	s_barrier
	s_waitcnt lgkmcnt(0)
	s_setprio 1
	s_waitcnt lgkmcnt(0)
	v_mfma_f32_16x16x32_bf16 v[62:65], v[156:159], v[172:175], v[62:65]
	v_mfma_f32_16x16x32_bf16 v[58:61], v[164:167], v[172:175], v[58:61]
	v_mfma_f32_16x16x32_bf16 v[54:57], v[156:159], v[192:195], v[54:57]
	v_mfma_f32_16x16x32_bf16 v[50:53], v[164:167], v[192:195], v[50:53]
	v_mfma_f32_16x16x32_bf16 v[38:41], v[156:159], v[200:203], v[38:41]
	v_mfma_f32_16x16x32_bf16 v[34:37], v[164:167], v[200:203], v[34:37]
	v_mfma_f32_16x16x32_bf16 v[22:25], v[156:159], v[208:211], v[22:25]
	v_mfma_f32_16x16x32_bf16 v[18:21], v[164:167], v[208:211], v[18:21]
	v_mfma_f32_16x16x32_bf16 v[62:65], v[160:163], v[188:191], v[62:65]
	v_mfma_f32_16x16x32_bf16 v[58:61], v[168:171], v[188:191], v[58:61]
	v_mfma_f32_16x16x32_bf16 v[54:57], v[160:163], v[196:199], v[54:57]
	v_mfma_f32_16x16x32_bf16 v[50:53], v[168:171], v[196:199], v[50:53]
	v_mfma_f32_16x16x32_bf16 v[38:41], v[160:163], v[204:207], v[38:41]
	v_mfma_f32_16x16x32_bf16 v[34:37], v[168:171], v[204:207], v[34:37]
	v_mfma_f32_16x16x32_bf16 v[22:25], v[160:163], v[212:215], v[22:25]
	v_mfma_f32_16x16x32_bf16 v[18:21], v[168:171], v[212:215], v[18:21]
	s_setprio 0
	s_barrier
; #define PG8_STAGE(bufoff, gbase, voff) do { _Pragma("unroll") for (int _i = 0; _i < 2; ++_i) \
;         __builtin_amdgcn_global_load_lds((const unsigned*)((const char*)(gbase) + (voff)[_i]), (LAS unsigned*)(lds + (bufoff) + ldsw + _i * 8192), 16, 0, 0); } while (0)
; #define PG8_LDA(dst, b, h) do { _Pragma("unroll") for (int m = 0; m < 4; ++m) _Pragma("unroll") for (int k = 0; k < 2; ++k) dst[m][k] = *(const LAS bf16x8*)(lds + PG8_SA(b, h) + aoff + m * 2048 + k * 1024); } while (0)
; #define PG8_LDB(dst, b, h) do { _Pragma("unroll") for (int n = 0; n < 2; ++n) _Pragma("unroll") for (int k = 0; k < 2; ++k) dst[n][k] = *(const LAS bf16x8*)(lds + PG8_SB(b, h) + boff + n * 2048 + k * 1024); } while (0)
; #define PG8_MMA(ai, bj, At, Bt) do { __builtin_amdgcn_s_setprio(1); _Pragma("unroll") for (int m = 0; m < 4; ++m) _Pragma("unroll") for (int n = 0; n < 2; ++n) _Pragma("unroll") for (int k = 0; k < 2; ++k) \
;         acc[ai][bj][m][n] = __builtin_amdgcn_mfma_f32_16x16x32_bf16(Bt[n][k], At[m][k], acc[ai][bj][m][n], 0, 0, 0); __builtin_amdgcn_s_setprio(0); } while (0)
; #define PG8_WAIT_V(n) asm volatile("s_waitcnt vmcnt(" #n ")" ::: "memory")
; #define PG8_WAIT_L(n) asm volatile("s_waitcnt lgkmcnt(" #n ")" ::: "memory")
; #define PG8_BAR __builtin_amdgcn_s_barrier()
; #define PG8_SCHED __builtin_amdgcn_sched_barrier(0)
; template <class Epi, class Sched>
; __device__ __forceinline__ void gemm_phase(LAS unsigned char* lds, const Gemm g, const Sched& S, const Epi& E) {
;     ...
;             PG8_STAGE(PG8_SB(0, 1), b2 + hstep, voffB);
;             PG8_WAIT_V(6); PG8_BAR; PG8_MMA(1, 1, At, B1); PG8_BAR;
;             PG8_LDB(B0, 1, 0); PG8_SCHED; PG8_LDA(At, 1, 0); PG8_STAGE(PG8_SA(0, 1), a2 + hstep, voffA);
;             PG8_WAIT_L(8); PG8_BAR; PG8_WAIT_L(0); PG8_MMA(0, 0, At, B0); PG8_BAR; PG8_SCHED;
;             PG8_LDB(B1, 1, 1); PG8_STAGE(PG8_SB(1, 0), b3, voffB);
;             PG8_BAR; PG8_WAIT_L(0); PG8_MMA(0, 1, At, B1); PG8_BAR;
;             PG8_LDA(At, 1, 1); PG8_STAGE(PG8_SA(1, 0), a3, voffA);
;             PG8_BAR; PG8_WAIT_L(0); PG8_MMA(1, 0, At, B0); PG8_BAR; PG8_SCHED;
	s_add_u32 s20, s66, 0xb0000
	s_addc_u32 s21, s67, 0
	s_add_i32 s19, s22, s9
	v_lshl_add_u64 v[156:157], s[20:21], 0, v[144:145]
	s_mov_b32 m0, s19
	s_nop 0
	global_load_lds_dwordx4 v[156:157], off
	v_lshl_add_u64 v[156:157], s[20:21], 0, v[140:141]
	s_add_i32 m0, s19, 0x2000
	s_nop 0
	global_load_lds_dwordx4 v[156:157], off
	s_waitcnt vmcnt(6)
	s_barrier
	s_setprio 1
	v_mfma_f32_16x16x32_bf16 v[46:49], v[216:219], v[172:175], v[46:49]
	v_add_u32_e32 v155, 0x18010, v152
	v_mfma_f32_16x16x32_bf16 v[42:45], v[224:227], v[172:175], v[42:45]
	ds_read_b128 v[156:159], v155
	v_mfma_f32_16x16x32_bf16 v[30:33], v[216:219], v[192:195], v[30:33]
	ds_read_b128 v[160:163], v155 offset:1024
	v_mfma_f32_16x16x32_bf16 v[26:29], v[224:227], v[192:195], v[26:29]
	ds_read_b128 v[164:167], v155 offset:2048
	v_mfma_f32_16x16x32_bf16 v[14:17], v[216:219], v[200:203], v[14:17]
	ds_read_b128 v[168:171], v155 offset:3072
	v_mfma_f32_16x16x32_bf16 v[10:13], v[224:227], v[200:203], v[10:13]
	v_mfma_f32_16x16x32_bf16 v[4:7], v[216:219], v[208:211], v[4:7]
	v_mfma_f32_16x16x32_bf16 v[0:3], v[224:227], v[208:211], v[0:3]
	v_mfma_f32_16x16x32_bf16 v[46:49], v[220:223], v[188:191], v[46:49]
	v_mfma_f32_16x16x32_bf16 v[42:45], v[228:231], v[188:191], v[42:45]
	v_mfma_f32_16x16x32_bf16 v[30:33], v[220:223], v[196:199], v[30:33]
	v_mfma_f32_16x16x32_bf16 v[26:29], v[228:231], v[196:199], v[26:29]
	v_mfma_f32_16x16x32_bf16 v[14:17], v[220:223], v[204:207], v[14:17]
	v_mfma_f32_16x16x32_bf16 v[10:13], v[228:231], v[204:207], v[10:13]
	v_mfma_f32_16x16x32_bf16 v[4:7], v[220:223], v[212:215], v[4:7]
	v_mfma_f32_16x16x32_bf16 v[0:3], v[228:231], v[212:215], v[0:3]
	s_setprio 0
	s_add_i32 s19, 16, 0x18000
	v_add_u32_e32 v155, s19, v152
	s_barrier
	s_add_u32 s20, s70, 0xb0000
	s_addc_u32 s21, s71, 0
	s_mov_b32 m0, s12
	v_lshl_add_u64 v[216:217], s[20:21], 0, v[146:147]
	ds_read_b128 v[172:175], v154 offset:32768
	ds_read_b128 v[188:191], v154 offset:33792
	ds_read_b128 v[192:195], v154 offset:34816
	ds_read_b128 v[196:199], v154 offset:35840
	ds_read_b128 v[200:203], v154 offset:36864
	ds_read_b128 v[204:207], v154 offset:37888
	ds_read_b128 v[208:211], v154 offset:38912
	ds_read_b128 v[212:215], v154 offset:39936
	global_load_lds_dwordx4 v[216:217], off
	v_lshl_add_u64 v[216:217], s[20:21], 0, v[142:143]
	s_mov_b32 m0, s13
	s_nop 0
	global_load_lds_dwordx4 v[216:217], off
	s_waitcnt lgkmcnt(8)
	s_barrier
	s_waitcnt lgkmcnt(0)
	s_setprio 1
	s_waitcnt lgkmcnt(0)
	v_mfma_f32_16x16x32_bf16 v[126:129], v[156:159], v[172:175], v[126:129]
	v_mfma_f32_16x16x32_bf16 v[122:125], v[164:167], v[172:175], v[122:125]
	v_mfma_f32_16x16x32_bf16 v[118:121], v[156:159], v[192:195], v[118:121]
	v_mfma_f32_16x16x32_bf16 v[114:117], v[164:167], v[192:195], v[114:117]
	v_mfma_f32_16x16x32_bf16 v[102:105], v[156:159], v[200:203], v[102:105]
	v_mfma_f32_16x16x32_bf16 v[98:101], v[164:167], v[200:203], v[98:101]
	v_mfma_f32_16x16x32_bf16 v[86:89], v[156:159], v[208:211], v[86:89]
	v_mfma_f32_16x16x32_bf16 v[82:85], v[164:167], v[208:211], v[82:85]
	v_mfma_f32_16x16x32_bf16 v[126:129], v[160:163], v[188:191], v[126:129]
	v_mfma_f32_16x16x32_bf16 v[122:125], v[168:171], v[188:191], v[122:125]
	v_mfma_f32_16x16x32_bf16 v[118:121], v[160:163], v[196:199], v[118:121]
	v_mfma_f32_16x16x32_bf16 v[114:117], v[168:171], v[196:199], v[114:117]
	v_mfma_f32_16x16x32_bf16 v[102:105], v[160:163], v[204:207], v[102:105]
	v_mfma_f32_16x16x32_bf16 v[98:101], v[168:171], v[204:207], v[98:101]
	v_mfma_f32_16x16x32_bf16 v[86:89], v[160:163], v[212:215], v[86:89]
	v_mfma_f32_16x16x32_bf16 v[82:85], v[168:171], v[212:215], v[82:85]
	s_setprio 0
	s_barrier
	s_add_i32 s22, 16, 0x1c000
	s_add_i32 s19, s19, s9
	v_add_u32_e32 v155, s22, v152
	v_lshl_add_u64 v[232:233], v[232:233], 0, s[94:95]
	s_mov_b32 m0, s19
	ds_read_b128 v[216:219], v155
	ds_read_b128 v[220:223], v155 offset:1024
	ds_read_b128 v[224:227], v155 offset:2048
	ds_read_b128 v[228:231], v155 offset:3072
	global_load_lds_dwordx4 v[232:233], off
	v_lshl_add_u64 v[232:233], v[234:235], 0, s[94:95]
	s_add_i32 m0, s19, 0x2000
	s_nop 0
	global_load_lds_dwordx4 v[232:233], off
	s_barrier
	s_waitcnt lgkmcnt(0)
	s_setprio 1
	s_waitcnt lgkmcnt(0)
	v_mfma_f32_16x16x32_bf16 v[110:113], v[216:219], v[172:175], v[110:113]
	v_mfma_f32_16x16x32_bf16 v[106:109], v[224:227], v[172:175], v[106:109]
	v_mfma_f32_16x16x32_bf16 v[94:97], v[216:219], v[192:195], v[94:97]
	v_mfma_f32_16x16x32_bf16 v[90:93], v[224:227], v[192:195], v[90:93]
	v_mfma_f32_16x16x32_bf16 v[78:81], v[216:219], v[200:203], v[78:81]
	v_mfma_f32_16x16x32_bf16 v[74:77], v[224:227], v[200:203], v[74:77]
	v_mfma_f32_16x16x32_bf16 v[70:73], v[216:219], v[208:211], v[70:73]
	v_mfma_f32_16x16x32_bf16 v[66:69], v[224:227], v[208:211], v[66:69]
	v_mfma_f32_16x16x32_bf16 v[110:113], v[220:223], v[188:191], v[110:113]
	v_mfma_f32_16x16x32_bf16 v[106:109], v[228:231], v[188:191], v[106:109]
	v_mfma_f32_16x16x32_bf16 v[94:97], v[220:223], v[196:199], v[94:97]
	v_mfma_f32_16x16x32_bf16 v[90:93], v[228:231], v[196:199], v[90:93]
	v_mfma_f32_16x16x32_bf16 v[78:81], v[220:223], v[204:207], v[78:81]
	v_mfma_f32_16x16x32_bf16 v[74:77], v[228:231], v[204:207], v[74:77]
	v_mfma_f32_16x16x32_bf16 v[70:73], v[220:223], v[212:215], v[70:73]
	v_mfma_f32_16x16x32_bf16 v[66:69], v[228:231], v[212:215], v[66:69]
	s_setprio 0
	s_mov_b32 m0, s14
	v_lshl_add_u64 v[232:233], v[236:237], 0, s[94:95]
	s_barrier
; #define PG8_STAGE(bufoff, gbase, voff) do { _Pragma("unroll") for (int _i = 0; _i < 2; ++_i) \
;         __builtin_amdgcn_global_load_lds((const unsigned*)((const char*)(gbase) + (voff)[_i]), (LAS unsigned*)(lds + (bufoff) + ldsw + _i * 8192), 16, 0, 0); } while (0)
; #define PG8_LDA(dst, b, h) do { _Pragma("unroll") for (int m = 0; m < 4; ++m) _Pragma("unroll") for (int k = 0; k < 2; ++k) dst[m][k] = *(const LAS bf16x8*)(lds + PG8_SA(b, h) + aoff + m * 2048 + k * 1024); } while (0)
; #define PG8_LDB(dst, b, h) do { _Pragma("unroll") for (int n = 0; n < 2; ++n) _Pragma("unroll") for (int k = 0; k < 2; ++k) dst[n][k] = *(const LAS bf16x8*)(lds + PG8_SB(b, h) + boff + n * 2048 + k * 1024); } while (0)
; #define PG8_MMA(ai, bj, At, Bt) do { __builtin_amdgcn_s_setprio(1); _Pragma("unroll") for (int m = 0; m < 4; ++m) _Pragma("unroll") for (int n = 0; n < 2; ++n) _Pragma("unroll") for (int k = 0; k < 2; ++k) \
;         acc[ai][bj][m][n] = __builtin_amdgcn_mfma_f32_16x16x32_bf16(Bt[n][k], At[m][k], acc[ai][bj][m][n], 0, 0, 0); __builtin_amdgcn_s_setprio(0); } while (0)
; #define PG8_WAIT_V(n) asm volatile("s_waitcnt vmcnt(" #n ")" ::: "memory")
; #define PG8_WAIT_L(n) asm volatile("s_waitcnt lgkmcnt(" #n ")" ::: "memory")
; #define PG8_BAR __builtin_amdgcn_s_barrier()
; #define PG8_SCHED __builtin_amdgcn_sched_barrier(0)
; template <class Epi, class Sched>
; __device__ __forceinline__ void gemm_phase(LAS unsigned char* lds, const Gemm g, const Sched& S, const Epi& E) {
;     ...
;             PG8_LDB(B0, 0, 0); PG8_SCHED; PG8_LDA(At, 0, 0); PG8_STAGE(PG8_SA(1, 1), a1 + hstep, voffA);
;     ...
;             PG8_LDA(At, 1, 1); PG8_STAGE(PG8_SA(1, 0), a3, voffA);
;             PG8_BAR; PG8_WAIT_L(0); PG8_MMA(1, 0, At, B0); PG8_BAR; PG8_SCHED;
;             PG8_STAGE(PG8_SB(1, 1), b3 + hstep, voffB);
;             PG8_WAIT_V(6); PG8_BAR; PG8_MMA(1, 1, At, B1); PG8_BAR;
;         }
	ds_read_b128 v[172:175], v154 offset:49152
	ds_read_b128 v[188:191], v154 offset:50176
	ds_read_b128 v[192:195], v154 offset:51200
	ds_read_b128 v[196:199], v154 offset:52224
	ds_read_b128 v[200:203], v154 offset:53248
	ds_read_b128 v[204:207], v154 offset:54272
	ds_read_b128 v[208:211], v154 offset:55296
	ds_read_b128 v[212:215], v154 offset:56320
	global_load_lds_dwordx4 v[232:233], off
	v_lshl_add_u64 v[232:233], v[238:239], 0, s[94:95]
	s_mov_b32 m0, s15
	s_nop 0
	global_load_lds_dwordx4 v[232:233], off
	s_barrier
	s_waitcnt lgkmcnt(0)
	s_setprio 1
	s_waitcnt lgkmcnt(0)
	v_mfma_f32_16x16x32_bf16 v[62:65], v[156:159], v[172:175], v[62:65]
	v_mfma_f32_16x16x32_bf16 v[58:61], v[164:167], v[172:175], v[58:61]
	v_mfma_f32_16x16x32_bf16 v[54:57], v[156:159], v[192:195], v[54:57]
	v_mfma_f32_16x16x32_bf16 v[50:53], v[164:167], v[192:195], v[50:53]
	v_mfma_f32_16x16x32_bf16 v[38:41], v[156:159], v[200:203], v[38:41]
	v_mfma_f32_16x16x32_bf16 v[34:37], v[164:167], v[200:203], v[34:37]
	v_mfma_f32_16x16x32_bf16 v[22:25], v[156:159], v[208:211], v[22:25]
	v_mfma_f32_16x16x32_bf16 v[18:21], v[164:167], v[208:211], v[18:21]
	v_mfma_f32_16x16x32_bf16 v[62:65], v[160:163], v[188:191], v[62:65]
	v_mfma_f32_16x16x32_bf16 v[58:61], v[168:171], v[188:191], v[58:61]
	v_mfma_f32_16x16x32_bf16 v[54:57], v[160:163], v[196:199], v[54:57]
	v_mfma_f32_16x16x32_bf16 v[50:53], v[168:171], v[196:199], v[50:53]
	v_mfma_f32_16x16x32_bf16 v[38:41], v[160:163], v[204:207], v[38:41]
	v_mfma_f32_16x16x32_bf16 v[34:37], v[168:171], v[204:207], v[34:37]
	v_mfma_f32_16x16x32_bf16 v[22:25], v[160:163], v[212:215], v[22:25]
	v_mfma_f32_16x16x32_bf16 v[18:21], v[168:171], v[212:215], v[18:21]
	s_setprio 0
	s_barrier
	s_add_u32 s20, s66, 0xb0080
	s_addc_u32 s21, s67, 0
	s_add_i32 s19, s22, s9
	v_lshl_add_u64 v[156:157], s[20:21], 0, v[144:145]
	s_mov_b32 m0, s19
	s_nop 0
	global_load_lds_dwordx4 v[156:157], off
	v_lshl_add_u64 v[156:157], s[20:21], 0, v[140:141]
	s_add_i32 m0, s19, 0x2000
	s_nop 0
	global_load_lds_dwordx4 v[156:157], off
	s_waitcnt vmcnt(6)
	s_barrier
	s_setprio 1
	v_mfma_f32_16x16x32_bf16 v[46:49], v[216:219], v[172:175], v[46:49]
	v_add_u32_e32 v155, 0x10010, v152
	v_mfma_f32_16x16x32_bf16 v[42:45], v[224:227], v[172:175], v[42:45]
	ds_read_b128 v[156:159], v155
	v_mfma_f32_16x16x32_bf16 v[30:33], v[216:219], v[192:195], v[30:33]
	ds_read_b128 v[160:163], v155 offset:1024
	v_mfma_f32_16x16x32_bf16 v[26:29], v[224:227], v[192:195], v[26:29]
	ds_read_b128 v[164:167], v155 offset:2048
	v_mfma_f32_16x16x32_bf16 v[14:17], v[216:219], v[200:203], v[14:17]
	ds_read_b128 v[168:171], v155 offset:3072
	v_mfma_f32_16x16x32_bf16 v[10:13], v[224:227], v[200:203], v[10:13]
	v_mfma_f32_16x16x32_bf16 v[4:7], v[216:219], v[208:211], v[4:7]
	v_mfma_f32_16x16x32_bf16 v[0:3], v[224:227], v[208:211], v[0:3]
	v_mfma_f32_16x16x32_bf16 v[46:49], v[220:223], v[188:191], v[46:49]
	v_mfma_f32_16x16x32_bf16 v[42:45], v[228:231], v[188:191], v[42:45]
	v_mfma_f32_16x16x32_bf16 v[30:33], v[220:223], v[196:199], v[30:33]
	v_mfma_f32_16x16x32_bf16 v[26:29], v[228:231], v[196:199], v[26:29]
	v_mfma_f32_16x16x32_bf16 v[14:17], v[220:223], v[204:207], v[14:17]
	v_mfma_f32_16x16x32_bf16 v[10:13], v[228:231], v[204:207], v[10:13]
	v_mfma_f32_16x16x32_bf16 v[4:7], v[220:223], v[212:215], v[4:7]
	v_mfma_f32_16x16x32_bf16 v[0:3], v[228:231], v[212:215], v[0:3]
	s_setprio 0
	s_add_i32 s18, s18, 2
	s_add_u32 s16, s16, 0x100
	s_addc_u32 s17, s17, 0
	s_cmp_gt_u32 s18, 41
	s_mov_b64 s[42:43], s[72:73]
	s_barrier
	s_cbranch_scc0 .LBB0_825
; __device__ __forceinline__ unsigned pk_bf16(float a, float b) { f32x2 v = {a, b}; bf2_t r = __builtin_convertvector(v, bf2_t); return __builtin_bit_cast(unsigned, r); }
; #define PG8_WAIT_V(n) asm volatile("s_waitcnt vmcnt(" #n ")" ::: "memory")
; #define PG8_BAR __builtin_amdgcn_s_barrier()
;     __device__ __forceinline__ void operator()(const f32x4 (&acc)[2][2][4][2], const Unit& u, int wr, int wc, int fr, int fq) const {
;         const int row0 = u.pm * BM + wr * 64 + fr; int colt = u.pn * BM; bf16_t* base = O;
;         if (split_cols) { const int t = colt / split_cols; base += (size_t)t * split_stride; colt -= t * split_cols; }
;         const int col0 = colt + wc * 32 + 8 * fq;
; #pragma unroll
;         for (int ai = 0; ai < 2; ++ai)
; #pragma unroll
;             for (int m = 0; m < 4; ++m) { const int row = row0 + ai * HALF + m * 16;
;                 bf16_t* rowp = slot_stride ? base + (size_t)(colt >> 7) * slot_stride + (size_t)row * 128 + wc * 32 + 8 * fq : base + (size_t)row * ldc + col0;
; #pragma unroll
;                 for (int bj = 0; bj < 2; ++bj) { const f32x4 v0 = acc[ai][bj][m][0], v1 = acc[ai][bj][m][1];
;                     u32x4 w; w.x = pk_bf16(v0[0], v0[1]); w.y = pk_bf16(v0[2], v0[3]); w.z = pk_bf16(v1[0], v1[1]); w.w = pk_bf16(v1[2], v1[3]);
;                     *(u32x4*)(rowp + (slot_stride ? (size_t)bj * slot_stride : (size_t)bj * HALF)) = w; } }
; template <class Epi, class Sched>
; __device__ __forceinline__ void gemm_phase(LAS unsigned char* lds, const Gemm g, const Sched& S, const Epi& E) {
;     ...
;         E(acc, cur, wr, wc, fr, fq); S.done(cur);
;         if (!has_next) break;
; #pragma unroll
;         for (int a = 0; a < 2; ++a)
; #pragma unroll
;             for (int b = 0; b < 2; ++b)
; #pragma unroll
;                 for (int m = 0; m < 4; ++m)
; #pragma unroll
;                     for (int n = 0; n < 2; ++n) acc[a][b][m][n] = (f32x4){0.f, 0.f, 0.f, 0.f};
;         cur = nxt; cA = nA; cB = nB; ++ui;
;     }
;     PG8_WAIT_V(0);
;     if (wr == 0) PG8_BAR;
;     PG8_BAR;
	s_waitcnt lgkmcnt(0)
	v_lshl_add_u32 v156, s78, 8, v9
	v_lshl_or_b32 v158, s75, 8, v153
	v_readlane_b32 s16, v244, 38
	v_ashrrev_i32_e32 v159, 31, v158
	v_readlane_b32 s17, v244, 39
	v_ashrrev_i32_e32 v157, 31, v156
	v_lshlrev_b64 v[160:161], 11, v[156:157]
	v_lshl_add_u64 v[158:159], v[158:159], 1, s[16:17]
	v_lshl_add_u64 v[160:161], v[158:159], 0, v[160:161]
	s_mov_b64 s[16:17], 0x40000
	v_cvt_pk_bf16_f32 v70, v70, v71
	v_cvt_pk_bf16_f32 v71, v72, v73
	v_cvt_pk_bf16_f32 v72, v66, v67
	v_lshl_add_u64 v[66:67], v[160:161], 0, s[16:17]
	s_mov_b32 s16, 0x40000
	v_cvt_pk_bf16_f32 v62, v62, v63
	v_cvt_pk_bf16_f32 v63, v64, v65
	v_cvt_pk_bf16_f32 v64, v58, v59
	v_add_co_u32_e32 v58, vcc, s16, v160
	v_cvt_pk_bf16_f32 v46, v46, v47
	v_cvt_pk_bf16_f32 v47, v48, v49
	v_cvt_pk_bf16_f32 v48, v42, v43
	v_cvt_pk_bf16_f32 v49, v44, v45
	s_mov_b64 s[16:17], 0x48000
	v_addc_co_u32_e32 v59, vcc, 0, v161, vcc
	global_store_dwordx4 v[66:67], v[46:49], off offset:256
	v_cvt_pk_bf16_f32 v30, v30, v31
	v_cvt_pk_bf16_f32 v31, v32, v33
	v_lshl_add_u64 v[46:47], v[160:161], 0, s[16:17]
	s_mov_b32 s16, 0x48000
	v_add_co_u32_e32 v48, vcc, s16, v160
	v_cvt_pk_bf16_f32 v32, v26, v27
	v_cvt_pk_bf16_f32 v33, v28, v29
	s_mov_b64 s[16:17], 0x50000
	v_cvt_pk_bf16_f32 v110, v110, v111
	v_cvt_pk_bf16_f32 v111, v112, v113
	v_cvt_pk_bf16_f32 v112, v106, v107
	v_or_b32_e32 v106, 16, v156
	v_addc_co_u32_e32 v49, vcc, 0, v161, vcc
	global_store_dwordx4 v[46:47], v[30:33], off offset:256
	v_ashrrev_i32_e32 v107, 31, v106
	v_cvt_pk_bf16_f32 v94, v94, v95
	v_lshl_add_u64 v[30:31], v[160:161], 0, s[16:17]
	s_mov_b32 s16, 0x50000
	v_cvt_pk_bf16_f32 v95, v96, v97
	v_cvt_pk_bf16_f32 v96, v90, v91
	v_or_b32_e32 v90, 32, v156
	v_add_co_u32_e32 v32, vcc, s16, v160
	v_cvt_pk_bf16_f32 v14, v14, v15
	v_cvt_pk_bf16_f32 v15, v16, v17
	v_cvt_pk_bf16_f32 v16, v10, v11
	v_cvt_pk_bf16_f32 v17, v12, v13
	s_mov_b64 s[16:17], 0x58000
	v_cvt_pk_bf16_f32 v113, v108, v109
	v_lshlrev_b64 v[106:107], 11, v[106:107]
	v_ashrrev_i32_e32 v91, 31, v90
	v_cvt_pk_bf16_f32 v78, v78, v79
	v_cvt_pk_bf16_f32 v79, v80, v81
	v_cvt_pk_bf16_f32 v80, v74, v75
	v_or_b32_e32 v74, 48, v156
	v_addc_co_u32_e32 v33, vcc, 0, v161, vcc
	global_store_dwordx4 v[30:31], v[14:17], off offset:256
	global_store_dwordx4 v[160:161], v[110:113], off offset:256
	v_cvt_pk_bf16_f32 v97, v92, v93
	v_lshl_add_u64 v[14:15], v[160:161], 0, s[16:17]
	s_mov_b32 s16, 0x58000
	v_lshl_add_u64 v[110:111], v[158:159], 0, v[106:107]
	v_lshlrev_b64 v[90:91], 11, v[90:91]
	v_ashrrev_i32_e32 v75, 31, v74
	v_add_co_u32_e32 v16, vcc, s16, v160
	global_store_dwordx4 v[110:111], v[94:97], off offset:256
	v_cvt_pk_bf16_f32 v81, v76, v77
	v_lshlrev_b64 v[74:75], 11, v[74:75]
	v_lshl_add_u64 v[94:95], v[158:159], 0, v[90:91]
	v_addc_co_u32_e32 v17, vcc, 0, v161, vcc
	v_readlane_b32 s70, v244, 55
	v_cvt_pk_bf16_f32 v126, v126, v127
	v_cvt_pk_bf16_f32 v127, v128, v129
	v_cvt_pk_bf16_f32 v128, v122, v123
	v_cvt_pk_bf16_f32 v129, v124, v125
	v_cvt_pk_bf16_f32 v106, v118, v119
	v_cvt_pk_bf16_f32 v107, v120, v121
	v_cvt_pk_bf16_f32 v108, v114, v115
	v_cvt_pk_bf16_f32 v109, v116, v117
	v_cvt_pk_bf16_f32 v90, v102, v103
	v_cvt_pk_bf16_f32 v91, v104, v105
	v_cvt_pk_bf16_f32 v92, v98, v99
	v_cvt_pk_bf16_f32 v93, v100, v101
	global_store_dwordx4 v[94:95], v[78:81], off offset:256
	v_cvt_pk_bf16_f32 v76, v82, v83
	v_cvt_pk_bf16_f32 v77, v84, v85
	v_lshl_add_u64 v[78:79], v[158:159], 0, v[74:75]
	v_cvt_pk_bf16_f32 v74, v86, v87
	v_cvt_pk_bf16_f32 v75, v88, v89
	v_cvt_pk_bf16_f32 v73, v68, v69
	v_cvt_pk_bf16_f32 v65, v60, v61
	v_cvt_pk_bf16_f32 v42, v54, v55
	v_cvt_pk_bf16_f32 v43, v56, v57
	v_cvt_pk_bf16_f32 v44, v50, v51
	v_cvt_pk_bf16_f32 v45, v52, v53
	v_cvt_pk_bf16_f32 v26, v38, v39
	v_cvt_pk_bf16_f32 v27, v40, v41
	v_cvt_pk_bf16_f32 v28, v34, v35
	v_cvt_pk_bf16_f32 v29, v36, v37
	v_cvt_pk_bf16_f32 v10, v22, v23
	v_cvt_pk_bf16_f32 v11, v24, v25
	v_cvt_pk_bf16_f32 v12, v18, v19
	v_cvt_pk_bf16_f32 v13, v20, v21
	v_cvt_pk_bf16_f32 v4, v4, v5
	v_cvt_pk_bf16_f32 v5, v6, v7
	v_cvt_pk_bf16_f32 v6, v0, v1
	v_cvt_pk_bf16_f32 v7, v2, v3
	s_and_b64 vcc, exec, s[38:39]
	s_mov_b32 s75, s85
	s_mov_b32 s78, s88
	s_mov_b64 s[72:73], s[0:1]
	s_mov_b64 s[42:43], s[40:41]
	v_readlane_b32 s71, v244, 56
	global_store_dwordx4 v[160:161], v[126:129], off
	global_store_dwordx4 v[110:111], v[106:109], off
	global_store_dwordx4 v[94:95], v[90:93], off
	global_store_dwordx4 v[78:79], v[74:77], off
	global_store_dwordx4 v[78:79], v[70:73], off offset:256
	global_store_dwordx4 v[58:59], v[62:65], off
	global_store_dwordx4 v[48:49], v[42:45], off
	global_store_dwordx4 v[32:33], v[26:29], off
	global_store_dwordx4 v[16:17], v[10:13], off
	global_store_dwordx4 v[14:15], v[4:7], off offset:256
	s_cbranch_vccz .LBB0_818
	s_waitcnt vmcnt(0)
	v_readlane_b32 s16, v244, 51
	s_cmpk_gt_u32 s6, 0xff
	v_readlane_b32 s17, v244, 52
	s_cbranch_scc1 .LBB0_829
	s_barrier
